# v33 + write-through (sc1) on the now row-contiguous dwordx4 stores of DFT stage 2 and SGU
# speedup vs baseline: 1.0268x; 1.0043x over previous
.LBB0_117:
	s_ashr_i32 s8, s22, 3
	s_abs_i32 s10, s8
	s_mul_hi_u32 s11, s10, s13
	s_mul_i32 s14, s11, s2
	s_sub_i32 s10, s10, s14
	s_ashr_i32 s9, s22, 31
	s_add_i32 s14, s11, 1
	s_sub_i32 s15, s10, s2
	s_cmp_ge_u32 s10, s2
	s_cselect_b32 s11, s14, s11
	s_cselect_b32 s10, s15, s10
	s_add_i32 s14, s11, 1
	s_cmp_ge_u32 s10, s2
	s_cselect_b32 s10, s14, s11
	s_xor_b32 s10, s10, s9
	s_sub_i32 s10, s10, s9
	s_mul_i32 s9, s10, s2
	s_sub_i32 s14, s8, s9
	s_mulk_i32 s8, 0x101
	s_ashr_i32 s9, s8, 31
	s_lshl_b64 s[8:9], s[8:9], 11
	s_add_u32 s11, s4, s8
	s_addc_u32 s15, s5, s9
	s_and_b32 s8, s18, 0x380
	s_lshl_b32 s8, s8, 1
	s_add_u32 s24, s11, s8
	s_addc_u32 s25, s15, 0
	v_lshl_add_u64 v[0:1], s[24:25], 0, v[154:155]
	v_lshl_add_u64 v[2:3], v[0:1], 0, v[38:39]
	global_load_dwordx2 v[72:73], v[2:3], off
	v_lshl_add_u64 v[2:3], v[0:1], 0, v[40:41]
	global_load_dwordx2 v[74:75], v[2:3], off
	v_lshl_add_u64 v[2:3], v[0:1], 0, v[42:43]
	global_load_dwordx2 v[76:77], v[2:3], off
	v_lshl_add_u64 v[2:3], v[0:1], 0, v[44:45]
	global_load_dwordx2 v[78:79], v[2:3], off
	v_lshl_add_u64 v[2:3], v[0:1], 0, v[46:47]
	global_load_dwordx2 v[80:81], v[2:3], off
	v_lshl_add_u64 v[2:3], v[0:1], 0, v[48:49]
	global_load_dwordx2 v[82:83], v[2:3], off
	v_lshl_add_u64 v[2:3], v[0:1], 0, v[50:51]
	global_load_dwordx2 v[84:85], v[2:3], off
	v_lshl_add_u64 v[2:3], v[0:1], 0, v[52:53]
	global_load_dwordx2 v[86:87], v[2:3], off
	v_lshl_add_u64 v[2:3], v[0:1], 0, v[54:55]
	global_load_dwordx2 v[88:89], v[2:3], off
	v_lshl_add_u64 v[2:3], v[0:1], 0, v[56:57]
	global_load_dwordx2 v[102:103], v[2:3], off
	v_lshl_add_u64 v[2:3], v[0:1], 0, v[58:59]
	global_load_dwordx2 v[104:105], v[2:3], off
	v_lshl_add_u64 v[2:3], v[0:1], 0, v[60:61]
	global_load_dwordx2 v[106:107], v[2:3], off
	v_lshl_add_u64 v[2:3], v[0:1], 0, v[62:63]
	global_load_dwordx2 v[108:109], v[2:3], off
	v_lshl_add_u64 v[2:3], v[0:1], 0, v[64:65]
	global_load_dwordx2 v[110:111], v[2:3], off
	v_lshl_add_u64 v[2:3], v[0:1], 0, v[66:67]
	global_load_dwordx2 v[112:113], v[2:3], off
	v_lshl_add_u64 v[0:1], v[0:1], 0, v[68:69]
	global_load_dwordx2 v[114:115], v[0:1], off
	s_ashr_i32 s11, s10, 31
	s_lshl_b64 s[10:11], s[10:11], s3
	s_ashr_i32 s15, s14, 31
	s_add_u32 s10, s10, s14
	v_add_u32_e32 v71, v90, v100
	s_addc_u32 s11, s11, s15
	s_mov_b32 s9, s96
	s_waitcnt vmcnt(14)
	ds_write2st64_b64 v71, v[72:73], v[74:75] offset1:9
	s_waitcnt vmcnt(12)
	ds_write2st64_b64 v71, v[76:77], v[78:79] offset0:18 offset1:27
	s_waitcnt vmcnt(10)
	ds_write2st64_b64 v71, v[80:81], v[82:83] offset0:36 offset1:45
	s_waitcnt vmcnt(8)
	ds_write2st64_b64 v71, v[84:85], v[86:87] offset0:54 offset1:63
	s_waitcnt vmcnt(6)
	ds_write2st64_b64 v71, v[88:89], v[102:103] offset0:72 offset1:81
	s_waitcnt vmcnt(4)
	ds_write2st64_b64 v71, v[104:105], v[106:107] offset0:90 offset1:99
	s_waitcnt vmcnt(2)
	ds_write2st64_b64 v71, v[108:109], v[110:111] offset0:108 offset1:117
	s_waitcnt vmcnt(1)
	ds_write_b64 v71, v[112:113] offset:64512
	s_waitcnt vmcnt(0)
	ds_write_b64 v101, v[114:115] offset:64512
	v_lshl_add_u64 v[72:73], s[10:11], 0, v[36:37]
	v_mov_b64_e32 v[74:75], s[92:93]
	v_mad_u64_u32 v[74:75], s[10:11], v72, s33, v[74:75]
	v_mad_i32_i24 v75, v73, s33, v75
	v_lshl_add_u64 v[74:75], v[74:75], 0, s[8:9]
	v_mov_b32_e32 v71, v155
	v_lshl_add_u64 v[74:75], v[74:75], 0, v[70:71]
	v_lshl_add_u64 v[102:103], v[74:75], 0, s[72:73]
	v_add_co_u32_e32 v74, vcc, s69, v74
	s_waitcnt lgkmcnt(0)
	s_nop 0
	v_addc_co_u32_e32 v75, vcc, 0, v75, vcc
	s_nop 0
	v_readfirstlane_b32 s98, v74
	v_readfirstlane_b32 s99, v75
	s_nop 4
	global_load_dwordx4 v[74:77], v184, s[98:99]
	s_add_u32 s98, s98, s100
	s_addc_u32 s99, s99, 0
	global_load_dwordx4 v[78:81], v184, s[98:99]
	s_add_u32 s98, s98, s100
	s_addc_u32 s99, s99, 0
	global_load_dwordx4 v[82:85], v184, s[98:99]
	s_add_u32 s98, s98, s100
	s_addc_u32 s99, s99, 0
	global_load_dwordx4 v[86:89], v184, s[98:99]
	s_barrier
	ds_read_b64_tr_b16 v[104:105], v91 offset:4608
	ds_read_b64_tr_b16 v[102:103], v91
	ds_read_b64_tr_b16 v[106:107], v91 offset:32
	ds_read_b64_tr_b16 v[108:109], v91 offset:4640
	ds_read_b64_tr_b16 v[110:111], v91 offset:64
	ds_read_b64_tr_b16 v[112:113], v91 offset:4672
	ds_read_b64_tr_b16 v[114:115], v91 offset:96
	ds_read_b64_tr_b16 v[116:117], v91 offset:4704
	ds_read_b64_tr_b16 v[118:119], v91 offset:128
	ds_read_b64_tr_b16 v[120:121], v91 offset:4736
	ds_read_b64_tr_b16 v[122:123], v91 offset:160
	ds_read_b64_tr_b16 v[124:125], v91 offset:4768
	ds_read_b64_tr_b16 v[126:127], v91 offset:192
	ds_read_b64_tr_b16 v[128:129], v91 offset:4800
	ds_read_b64_tr_b16 v[130:131], v91 offset:224
	ds_read_b64_tr_b16 v[132:133], v91 offset:4832
	ds_read_b64_tr_b16 v[134:135], v91 offset:9216
	ds_read_b64_tr_b16 v[136:137], v91 offset:13824
	ds_read_b64_tr_b16 v[138:139], v91 offset:9248
	ds_read_b64_tr_b16 v[140:141], v91 offset:13856
	ds_read_b64_tr_b16 v[142:143], v91 offset:9280
	ds_read_b64_tr_b16 v[144:145], v91 offset:13888
	ds_read_b64_tr_b16 v[146:147], v91 offset:9312
	ds_read_b64_tr_b16 v[148:149], v91 offset:13920
	ds_read_b64_tr_b16 v[156:157], v91 offset:9344
	ds_read_b64_tr_b16 v[158:159], v91 offset:13952
	ds_read_b64_tr_b16 v[160:161], v91 offset:9376
	ds_read_b64_tr_b16 v[162:163], v91 offset:13984
	ds_read_b64_tr_b16 v[164:165], v91 offset:9408
	ds_read_b64_tr_b16 v[166:167], v91 offset:14016
	ds_read_b64_tr_b16 v[168:169], v91 offset:9440
	ds_read_b64_tr_b16 v[170:171], v91 offset:14048
	s_waitcnt vmcnt(22) lgkmcnt(14)
	v_mfma_f32_16x16x32_bf16 v[102:105], v[102:105], v[238:241], 0
	v_mfma_f32_16x16x32_bf16 v[106:109], v[106:109], v[238:241], 0
	v_mfma_f32_16x16x32_bf16 v[110:113], v[110:113], v[238:241], 0
	v_mfma_f32_16x16x32_bf16 v[114:117], v[114:117], v[238:241], 0
	v_mfma_f32_16x16x32_bf16 v[118:121], v[118:121], v[238:241], 0
	v_mfma_f32_16x16x32_bf16 v[122:125], v[122:125], v[238:241], 0
	v_mfma_f32_16x16x32_bf16 v[126:129], v[126:129], v[238:241], 0
	v_mfma_f32_16x16x32_bf16 v[28:31], v[130:133], v[238:241], 0
	ds_read_b64_tr_b16 v[130:131], v91 offset:18432
	ds_read_b64_tr_b16 v[172:173], v91 offset:18464
	ds_read_b64_tr_b16 v[176:177], v91 offset:18496
	ds_read_b64_tr_b16 v[180:181], v91 offset:18528
	ds_read_b64_tr_b16 v[132:133], v91 offset:23040
	ds_read_b64_tr_b16 v[174:175], v91 offset:23072
	ds_read_b64_tr_b16 v[178:179], v91 offset:23104
	ds_read_b64_tr_b16 v[182:183], v91 offset:23136
	ds_read_b64_tr_b16 v[188:189], v91 offset:18560
	ds_read_b64_tr_b16 v[192:193], v91 offset:18592
	ds_read_b64_tr_b16 v[202:203], v91 offset:18624
	ds_read_b64_tr_b16 v[206:207], v91 offset:18656
	ds_read_b64_tr_b16 v[190:191], v91 offset:23168
	ds_read_b64_tr_b16 v[194:195], v91 offset:23200
	ds_read_b64_tr_b16 v[204:205], v91 offset:23232
	ds_read_b64_tr_b16 v[208:209], v91 offset:23264
	s_waitcnt vmcnt(20)
	v_mfma_f32_16x16x32_bf16 v[102:105], v[134:137], v[234:237], v[102:105]
	s_waitcnt lgkmcnt(14)
	v_mfma_f32_16x16x32_bf16 v[106:109], v[138:141], v[234:237], v[106:109]
	v_mfma_f32_16x16x32_bf16 v[110:113], v[142:145], v[234:237], v[110:113]
	v_mfma_f32_16x16x32_bf16 v[114:117], v[146:149], v[234:237], v[114:117]
	v_mfma_f32_16x16x32_bf16 v[118:121], v[156:159], v[234:237], v[118:121]
	v_mfma_f32_16x16x32_bf16 v[122:125], v[160:163], v[234:237], v[122:125]
	v_mfma_f32_16x16x32_bf16 v[126:129], v[164:167], v[234:237], v[126:129]
	v_mfma_f32_16x16x32_bf16 v[24:27], v[168:171], v[234:237], v[28:31]
	s_nop 2
	ds_read_b64_tr_b16 v[28:29], v91 offset:27648
	ds_read_b64_tr_b16 v[134:135], v91 offset:27680
	ds_read_b64_tr_b16 v[138:139], v91 offset:27712
	ds_read_b64_tr_b16 v[142:143], v91 offset:27744
	ds_read_b64_tr_b16 v[30:31], v91 offset:32256
	ds_read_b64_tr_b16 v[136:137], v91 offset:32288
	ds_read_b64_tr_b16 v[140:141], v91 offset:32320
	ds_read_b64_tr_b16 v[144:145], v91 offset:32352
	ds_read_b64_tr_b16 v[146:147], v91 offset:27776
	ds_read_b64_tr_b16 v[156:157], v91 offset:27808
	ds_read_b64_tr_b16 v[160:161], v91 offset:27840
	ds_read_b64_tr_b16 v[164:165], v91 offset:27872
	ds_read_b64_tr_b16 v[148:149], v91 offset:32384
	ds_read_b64_tr_b16 v[158:159], v91 offset:32416
	ds_read_b64_tr_b16 v[162:163], v91 offset:32448
	ds_read_b64_tr_b16 v[166:167], v91 offset:32480
	s_waitcnt vmcnt(18) lgkmcnt(14)
	v_mfma_f32_16x16x32_bf16 v[102:105], v[130:133], v[230:233], v[102:105]
	v_mfma_f32_16x16x32_bf16 v[106:109], v[172:175], v[230:233], v[106:109]
	v_mfma_f32_16x16x32_bf16 v[110:113], v[176:179], v[230:233], v[110:113]
	v_mfma_f32_16x16x32_bf16 v[114:117], v[180:183], v[230:233], v[114:117]
	v_mfma_f32_16x16x32_bf16 v[118:121], v[188:191], v[230:233], v[118:121]
	v_mfma_f32_16x16x32_bf16 v[122:125], v[192:195], v[230:233], v[122:125]
	v_mfma_f32_16x16x32_bf16 v[126:129], v[202:205], v[230:233], v[126:129]
	v_mfma_f32_16x16x32_bf16 v[20:23], v[206:209], v[230:233], v[24:27]
	s_nop 2
	ds_read_b64_tr_b16 v[24:25], v91 offset:36864
	ds_read_b64_tr_b16 v[130:131], v91 offset:36896
	ds_read_b64_tr_b16 v[168:169], v91 offset:36928
	ds_read_b64_tr_b16 v[172:173], v91 offset:36960
	ds_read_b64_tr_b16 v[26:27], v91 offset:41472
	ds_read_b64_tr_b16 v[132:133], v91 offset:41504
	ds_read_b64_tr_b16 v[170:171], v91 offset:41536
	ds_read_b64_tr_b16 v[174:175], v91 offset:41568
	ds_read_b64_tr_b16 v[176:177], v91 offset:36992
	ds_read_b64_tr_b16 v[180:181], v91 offset:37024
	ds_read_b64_tr_b16 v[188:189], v91 offset:37056
	ds_read_b64_tr_b16 v[192:193], v91 offset:37088
	ds_read_b64_tr_b16 v[178:179], v91 offset:41600
	ds_read_b64_tr_b16 v[182:183], v91 offset:41632
	ds_read_b64_tr_b16 v[190:191], v91 offset:41664
	ds_read_b64_tr_b16 v[194:195], v91 offset:41696
	s_waitcnt vmcnt(16) lgkmcnt(14)
	v_mfma_f32_16x16x32_bf16 v[28:31], v[28:31], v[226:229], v[102:105]
	v_mfma_f32_16x16x32_bf16 v[102:105], v[134:137], v[226:229], v[106:109]
	v_mfma_f32_16x16x32_bf16 v[106:109], v[138:141], v[226:229], v[110:113]
	v_mfma_f32_16x16x32_bf16 v[110:113], v[142:145], v[226:229], v[114:117]
	v_mfma_f32_16x16x32_bf16 v[114:117], v[146:149], v[226:229], v[118:121]
	v_mfma_f32_16x16x32_bf16 v[118:121], v[156:159], v[226:229], v[122:125]
	v_mfma_f32_16x16x32_bf16 v[122:125], v[160:163], v[226:229], v[126:129]
	v_mfma_f32_16x16x32_bf16 v[16:19], v[164:167], v[226:229], v[20:23]
	s_nop 2
	ds_read_b64_tr_b16 v[20:21], v91 offset:46080
	ds_read_b64_tr_b16 v[126:127], v91 offset:46112
	ds_read_b64_tr_b16 v[134:135], v91 offset:46144
	ds_read_b64_tr_b16 v[138:139], v91 offset:46176
	ds_read_b64_tr_b16 v[22:23], v91 offset:50688
	ds_read_b64_tr_b16 v[128:129], v91 offset:50720
	ds_read_b64_tr_b16 v[136:137], v91 offset:50752
	ds_read_b64_tr_b16 v[140:141], v91 offset:50784
	ds_read_b64_tr_b16 v[142:143], v91 offset:46208
	ds_read_b64_tr_b16 v[146:147], v91 offset:46240
	ds_read_b64_tr_b16 v[156:157], v91 offset:46272
	ds_read_b64_tr_b16 v[160:161], v91 offset:46304
	ds_read_b64_tr_b16 v[144:145], v91 offset:50816
	ds_read_b64_tr_b16 v[148:149], v91 offset:50848
	ds_read_b64_tr_b16 v[158:159], v91 offset:50880
	ds_read_b64_tr_b16 v[162:163], v91 offset:50912
	s_waitcnt vmcnt(14) lgkmcnt(14)
	v_mfma_f32_16x16x32_bf16 v[24:27], v[24:27], v[222:225], v[28:31]
	v_mfma_f32_16x16x32_bf16 v[28:31], v[130:133], v[222:225], v[102:105]
	v_mfma_f32_16x16x32_bf16 v[102:105], v[168:171], v[222:225], v[106:109]
	v_mfma_f32_16x16x32_bf16 v[106:109], v[172:175], v[222:225], v[110:113]
	v_mfma_f32_16x16x32_bf16 v[110:113], v[176:179], v[222:225], v[114:117]
	v_mfma_f32_16x16x32_bf16 v[114:117], v[180:183], v[222:225], v[118:121]
	v_mfma_f32_16x16x32_bf16 v[118:121], v[188:191], v[222:225], v[122:125]
	v_mfma_f32_16x16x32_bf16 v[12:15], v[192:195], v[222:225], v[16:19]
	s_nop 2
	ds_read_b64_tr_b16 v[16:17], v91 offset:55296
	ds_read_b64_tr_b16 v[122:123], v91 offset:55328
	ds_read_b64_tr_b16 v[130:131], v91 offset:55360
	ds_read_b64_tr_b16 v[164:165], v91 offset:55392
	ds_read_b64_tr_b16 v[18:19], v91 offset:59904
	ds_read_b64_tr_b16 v[124:125], v91 offset:59936
	ds_read_b64_tr_b16 v[132:133], v91 offset:59968
	ds_read_b64_tr_b16 v[166:167], v91 offset:60000
	ds_read_b64_tr_b16 v[168:169], v91 offset:55424
	ds_read_b64_tr_b16 v[172:173], v91 offset:55456
	ds_read_b64_tr_b16 v[176:177], v91 offset:55488
	ds_read_b64_tr_b16 v[180:181], v91 offset:55520
	ds_read_b64_tr_b16 v[170:171], v91 offset:60032
	ds_read_b64_tr_b16 v[174:175], v91 offset:60064
	ds_read_b64_tr_b16 v[178:179], v91 offset:60096
	ds_read_b64_tr_b16 v[182:183], v91 offset:60128
	s_waitcnt vmcnt(12) lgkmcnt(14)
	v_mfma_f32_16x16x32_bf16 v[20:23], v[20:23], v[218:221], v[24:27]
	v_mfma_f32_16x16x32_bf16 v[24:27], v[126:129], v[218:221], v[28:31]
	v_mfma_f32_16x16x32_bf16 v[28:31], v[134:137], v[218:221], v[102:105]
	v_mfma_f32_16x16x32_bf16 v[102:105], v[138:141], v[218:221], v[106:109]
	v_mfma_f32_16x16x32_bf16 v[106:109], v[142:145], v[218:221], v[110:113]
	v_mfma_f32_16x16x32_bf16 v[110:113], v[146:149], v[218:221], v[114:117]
	v_mfma_f32_16x16x32_bf16 v[114:117], v[156:159], v[218:221], v[118:121]
	v_mfma_f32_16x16x32_bf16 v[8:11], v[160:163], v[218:221], v[12:15]
	s_nop 2
	ds_read_b64_tr_b16 v[12:13], v91 offset:64512
	ds_read_b64_tr_b16 v[118:119], v91 offset:64544
	ds_read_b64_tr_b16 v[126:127], v91 offset:64576
	ds_read_b64_tr_b16 v[134:135], v91 offset:64608
	ds_read_b64_tr_b16 v[14:15], v92
	ds_read_b64_tr_b16 v[120:121], v93
	ds_read_b64_tr_b16 v[128:129], v94
	ds_read_b64_tr_b16 v[136:137], v95
	ds_read_b64_tr_b16 v[138:139], v91 offset:64640
	ds_read_b64_tr_b16 v[142:143], v91 offset:64672
	ds_read_b64_tr_b16 v[146:147], v91 offset:64704
	ds_read_b64_tr_b16 v[156:157], v91 offset:64736
	ds_read_b64_tr_b16 v[140:141], v96
	ds_read_b64_tr_b16 v[144:145], v97
	ds_read_b64_tr_b16 v[148:149], v98
	ds_read_b64_tr_b16 v[158:159], v99
	s_waitcnt vmcnt(10) lgkmcnt(14)
	v_mfma_f32_16x16x32_bf16 v[16:19], v[16:19], v[214:217], v[20:23]
	v_mfma_f32_16x16x32_bf16 v[20:23], v[122:125], v[214:217], v[24:27]
	v_mfma_f32_16x16x32_bf16 v[24:27], v[130:133], v[214:217], v[28:31]
	v_mfma_f32_16x16x32_bf16 v[28:31], v[164:167], v[214:217], v[102:105]
	v_mfma_f32_16x16x32_bf16 v[102:105], v[168:171], v[214:217], v[106:109]
	v_mfma_f32_16x16x32_bf16 v[106:109], v[172:175], v[214:217], v[110:113]
	v_mfma_f32_16x16x32_bf16 v[110:113], v[176:179], v[214:217], v[114:117]
	v_mfma_f32_16x16x32_bf16 v[4:7], v[180:183], v[214:217], v[8:11]
	s_waitcnt vmcnt(8) lgkmcnt(11)
	v_mfma_f32_16x16x32_bf16 v[8:11], v[12:15], v[210:213], v[16:19]
	s_waitcnt lgkmcnt(10)
	v_mfma_f32_16x16x32_bf16 v[12:15], v[118:121], v[210:213], v[20:23]
	s_waitcnt lgkmcnt(9)
	v_mfma_f32_16x16x32_bf16 v[16:19], v[126:129], v[210:213], v[24:27]
	s_waitcnt lgkmcnt(8)
	v_mfma_f32_16x16x32_bf16 v[20:23], v[134:137], v[210:213], v[28:31]
	s_waitcnt lgkmcnt(3)
	v_mfma_f32_16x16x32_bf16 v[24:27], v[138:141], v[210:213], v[102:105]
	s_waitcnt lgkmcnt(2)
	v_mfma_f32_16x16x32_bf16 v[28:31], v[142:145], v[210:213], v[106:109]
	s_waitcnt lgkmcnt(1)
	v_mfma_f32_16x16x32_bf16 v[102:105], v[146:149], v[210:213], v[110:113]
	s_waitcnt lgkmcnt(0)
	v_mfma_f32_16x16x32_bf16 v[0:3], v[156:159], v[210:213], v[4:7]
	s_nop 2
	s_waitcnt vmcnt(0)
	ds_write_b128 v185, v[74:77]
	ds_write_b128 v185, v[78:81] offset:1152
	ds_write_b128 v185, v[82:85] offset:2304
	ds_write_b128 v185, v[86:89] offset:3456
	s_waitcnt lgkmcnt(0)
	ds_read_b64 v[88:89], v186
	ds_read_b64 v[86:87], v186 offset:32
	ds_read_b64 v[84:85], v186 offset:64
	ds_read_b64 v[82:83], v186 offset:96
	ds_read_b64 v[80:81], v186 offset:128
	ds_read_b64 v[78:79], v186 offset:160
	ds_read_b64 v[76:77], v186 offset:192
	ds_read_b64 v[74:75], v186 offset:224
	s_waitcnt lgkmcnt(0)
	v_mov_b64_e32 v[4:5], s[38:39]
	v_mad_u64_u32 v[4:5], s[10:11], v72, s34, v[4:5]
	v_pk_mul_f32 v[6:7], v[32:33], v[8:9]
	s_waitcnt vmcnt(7)
	v_lshlrev_b32_e32 v8, 16, v88
	v_and_b32_e32 v9, 0xffff0000, v88
	v_mad_i32_i24 v5, v73, s34, v5
	v_pk_mul_f32 v[6:7], v[6:7], v[8:9]
	v_pk_mul_f32 v[8:9], v[32:33], v[10:11]
	v_lshlrev_b32_e32 v10, 16, v89
	v_and_b32_e32 v11, 0xffff0000, v89
	v_lshl_add_u64 v[4:5], v[4:5], 0, s[8:9]
	v_pk_mul_f32 v[8:9], v[8:9], v[10:11]
	v_lshl_add_u64 v[4:5], v[4:5], 0, v[70:71]
	v_cvt_pk_bf16_f32 v6, v6, v7
	v_cvt_pk_bf16_f32 v7, v8, v9
	ds_write_b64 v186, v[6:7]
	v_pk_mul_f32 v[6:7], v[32:33], v[12:13]
	s_waitcnt vmcnt(7)
	v_lshlrev_b32_e32 v8, 16, v86
	v_and_b32_e32 v9, 0xffff0000, v86
	v_pk_mul_f32 v[6:7], v[6:7], v[8:9]
	v_pk_mul_f32 v[8:9], v[32:33], v[14:15]
	v_lshlrev_b32_e32 v10, 16, v87
	v_and_b32_e32 v11, 0xffff0000, v87
	v_pk_mul_f32 v[8:9], v[8:9], v[10:11]
	v_cvt_pk_bf16_f32 v6, v6, v7
	v_cvt_pk_bf16_f32 v7, v8, v9
	ds_write_b64 v186, v[6:7] offset:32
	v_pk_mul_f32 v[6:7], v[32:33], v[16:17]
	s_waitcnt vmcnt(7)
	v_lshlrev_b32_e32 v8, 16, v84
	v_and_b32_e32 v9, 0xffff0000, v84
	v_pk_mul_f32 v[6:7], v[6:7], v[8:9]
	v_pk_mul_f32 v[8:9], v[32:33], v[18:19]
	v_lshlrev_b32_e32 v10, 16, v85
	v_and_b32_e32 v11, 0xffff0000, v85
	v_pk_mul_f32 v[8:9], v[8:9], v[10:11]
	v_cvt_pk_bf16_f32 v6, v6, v7
	v_cvt_pk_bf16_f32 v7, v8, v9
	ds_write_b64 v186, v[6:7] offset:64
	v_pk_mul_f32 v[6:7], v[32:33], v[20:21]
	s_waitcnt vmcnt(7)
	v_lshlrev_b32_e32 v8, 16, v82
	v_and_b32_e32 v9, 0xffff0000, v82
	v_pk_mul_f32 v[6:7], v[6:7], v[8:9]
	v_pk_mul_f32 v[8:9], v[32:33], v[22:23]
	v_lshlrev_b32_e32 v10, 16, v83
	v_and_b32_e32 v11, 0xffff0000, v83
	v_pk_mul_f32 v[8:9], v[8:9], v[10:11]
	v_cvt_pk_bf16_f32 v6, v6, v7
	v_cvt_pk_bf16_f32 v7, v8, v9
	ds_write_b64 v186, v[6:7] offset:96
	v_pk_mul_f32 v[6:7], v[32:33], v[24:25]
	s_waitcnt vmcnt(7)
	v_lshlrev_b32_e32 v8, 16, v80
	v_and_b32_e32 v9, 0xffff0000, v80
	v_pk_mul_f32 v[6:7], v[6:7], v[8:9]
	v_pk_mul_f32 v[8:9], v[32:33], v[26:27]
	v_lshlrev_b32_e32 v10, 16, v81
	v_and_b32_e32 v11, 0xffff0000, v81
	v_pk_mul_f32 v[8:9], v[8:9], v[10:11]
	v_cvt_pk_bf16_f32 v6, v6, v7
	v_cvt_pk_bf16_f32 v7, v8, v9
	ds_write_b64 v186, v[6:7] offset:128
	v_pk_mul_f32 v[6:7], v[32:33], v[28:29]
	s_waitcnt vmcnt(7)
	v_lshlrev_b32_e32 v8, 16, v78
	v_and_b32_e32 v9, 0xffff0000, v78
	v_pk_mul_f32 v[6:7], v[6:7], v[8:9]
	v_pk_mul_f32 v[8:9], v[32:33], v[30:31]
	v_lshlrev_b32_e32 v10, 16, v79
	v_and_b32_e32 v11, 0xffff0000, v79
	v_pk_mul_f32 v[8:9], v[8:9], v[10:11]
	v_cvt_pk_bf16_f32 v6, v6, v7
	v_cvt_pk_bf16_f32 v7, v8, v9
	ds_write_b64 v186, v[6:7] offset:160
	v_pk_mul_f32 v[6:7], v[32:33], v[102:103]
	s_waitcnt vmcnt(7)
	v_lshlrev_b32_e32 v8, 16, v76
	v_and_b32_e32 v9, 0xffff0000, v76
	v_pk_mul_f32 v[6:7], v[6:7], v[8:9]
	v_pk_mul_f32 v[8:9], v[32:33], v[104:105]
	v_lshlrev_b32_e32 v10, 16, v77
	v_and_b32_e32 v11, 0xffff0000, v77
	v_pk_mul_f32 v[8:9], v[8:9], v[10:11]
	v_cvt_pk_bf16_f32 v6, v6, v7
	v_cvt_pk_bf16_f32 v7, v8, v9
	ds_write_b64 v186, v[6:7] offset:192
	v_pk_mul_f32 v[0:1], v[32:33], v[0:1]
	s_waitcnt vmcnt(7)
	v_lshlrev_b32_e32 v6, 16, v74
	v_and_b32_e32 v7, 0xffff0000, v74
	v_pk_mul_f32 v[0:1], v[0:1], v[6:7]
	v_pk_mul_f32 v[2:3], v[32:33], v[2:3]
	v_lshlrev_b32_e32 v6, 16, v75
	v_and_b32_e32 v7, 0xffff0000, v75
	v_pk_mul_f32 v[2:3], v[2:3], v[6:7]
	s_add_i32 s22, s22, s94
	s_add_i32 s18, s18, s29
	v_cvt_pk_bf16_f32 v0, v0, v1
	v_cvt_pk_bf16_f32 v1, v2, v3
	s_cmpk_gt_i32 s22, 0x3ff
	ds_write_b64 v186, v[0:1] offset:224
	s_nop 0
	v_readfirstlane_b32 s98, v4
	v_readfirstlane_b32 s99, v5
	s_waitcnt lgkmcnt(0)
	ds_read_b128 v[74:77], v185
	ds_read_b128 v[78:81], v185 offset:1152
	ds_read_b128 v[82:85], v185 offset:2304
	ds_read_b128 v[86:89], v185 offset:3456
	s_waitcnt lgkmcnt(3)
	global_store_dwordx4 v197, v[74:77], s[98:99] offset:2048 sc1
	s_waitcnt lgkmcnt(2)
	s_add_u32 s98, s98, s101
	s_addc_u32 s99, s99, 0
	global_store_dwordx4 v197, v[78:81], s[98:99] offset:2048 sc1
	s_waitcnt lgkmcnt(1)
	s_add_u32 s98, s98, s101
	s_addc_u32 s99, s99, 0
	global_store_dwordx4 v197, v[82:85], s[98:99] offset:2048 sc1
	s_waitcnt lgkmcnt(0)
	s_add_u32 s98, s98, s101
	s_addc_u32 s99, s99, 0
	global_store_dwordx4 v197, v[86:89], s[98:99] offset:2048 sc1
	s_cmpk_gt_i32 s22, 0x3ff
	s_barrier
	s_cbranch_scc0 .LBB0_117

.LBB0_125:
	s_and_b32 s10, s2, 0xffffff80
	v_add_u32_e32 v2, s10, v98
	v_mov_b64_e32 v[0:1], s[92:93]
	s_and_b32 s11, s3, 3
	v_mad_i64_i32 v[0:1], s[8:9], v2, s33, v[0:1]
	s_lshl_b32 s8, s11, 9
	s_mov_b32 s9, s96
	v_lshl_add_u64 v[0:1], v[0:1], 0, s[8:9]
	v_lshl_add_u64 v[20:21], v[0:1], 0, v[154:155]
	global_load_dwordx4 v[22:25], v[20:21], off offset:2048
	s_mov_b32 s25, s96
	s_mov_b32 s27, s96
	s_lshl_b32 s24, s11, 15
	s_lshl_b32 s26, s11, 10
	v_add_co_u32_e32 v26, vcc, s35, v20
	v_lshl_add_u64 v[88:89], v[82:83], 0, s[24:25]
	v_lshl_add_u64 v[12:13], v[84:85], 0, s[26:27]
	v_addc_co_u32_e32 v27, vcc, 0, v21, vcc
	global_load_dwordx2 v[4:5], v[88:89], off
	global_load_dwordx2 v[6:7], v[88:89], off offset:32
	global_load_dwordx2 v[0:1], v[88:89], off offset:64
	global_load_dwordx2 v[2:3], v[88:89], off offset:96
	global_load_dwordx4 v[8:11], v[12:13], off offset:16
	s_nop 0
	global_load_dwordx4 v[12:15], v[12:13], off
	s_nop 0
	global_load_dwordx4 v[72:75], v[20:21], off
	global_load_dwordx4 v[16:19], v[26:27], off offset:2304
	global_load_dwordx4 v[56:59], v[26:27], off offset:256
	v_add_co_u32_e32 v28, vcc, s12, v20
	s_mov_b32 s13, 0xf000
	s_nop 0
	v_addc_co_u32_e32 v29, vcc, 0, v21, vcc
	v_add_co_u32_e32 v26, vcc, s13, v20
	global_load_dwordx4 v[76:79], v[28:29], off offset:2560
	global_load_dwordx4 v[44:47], v[28:29], off offset:512
	v_addc_co_u32_e32 v27, vcc, 0, v21, vcc
	global_load_dwordx4 v[68:71], v[26:27], off offset:2816
	global_load_dwordx4 v[32:35], v[26:27], off offset:768
	s_mov_b32 s13, 0x14000
	v_add_co_u32_e32 v28, vcc, s13, v20
	s_mov_b32 s13, 0x19000
	s_nop 0
	v_addc_co_u32_e32 v29, vcc, 0, v21, vcc
	v_add_co_u32_e32 v26, vcc, s13, v20
	s_mov_b32 s13, 0x1e000
	s_waitcnt vmcnt(13)
	v_and_b32_e32 v97, 0xffff0000, v22
	v_lshlrev_b32_e32 v94, 16, v23
	v_lshlrev_b32_e32 v96, 16, v22
	v_mul_f32_e32 v36, v97, v97
	v_and_b32_e32 v95, 0xffff0000, v23
	v_add_f32_e32 v27, 0, v96
	v_mov_b32_e32 v30, v94
	v_mov_b32_e32 v31, v97
	v_pk_fma_f32 v[36:37], v[96:97], v[96:97], v[36:37] op_sel_hi:[1,1,0]
	v_lshlrev_b32_e32 v92, 16, v24
	v_mul_f32_e32 v38, v95, v95
	v_add_f32_e32 v27, v27, v97
	v_pk_fma_f32 v[30:31], v[30:31], v[30:31], v[36:37]
	v_lshlrev_b32_e32 v90, 16, v25
	v_and_b32_e32 v91, 0xffff0000, v25
	v_and_b32_e32 v93, 0xffff0000, v24
	v_mov_b32_e32 v24, v92
	v_mov_b32_e32 v25, v95
	v_add_f32_e32 v27, v27, v94
	v_pk_add_f32 v[30:31], v[38:39], v[30:31] op_sel_hi:[0,1]
	v_mul_f32_e32 v40, v93, v93
	v_add_f32_e32 v27, v27, v95
	v_pk_fma_f32 v[24:25], v[24:25], v[24:25], v[30:31]
	v_mov_b32_e32 v22, v90
	v_mov_b32_e32 v23, v93
	v_add_f32_e32 v27, v27, v92
	v_pk_add_f32 v[24:25], v[40:41], v[24:25] op_sel_hi:[0,1]
	v_add_f32_e32 v27, v27, v93
	v_pk_fma_f32 v[22:23], v[22:23], v[22:23], v[24:25]
	v_mul_f32_e32 v42, v91, v91
	v_add_f32_e32 v43, v27, v90
	v_mov_b32_e32 v23, v91
	v_pk_add_f32 v[22:23], v[42:43], v[22:23]
	ds_bpermute_b32 v25, v100, v23
	ds_bpermute_b32 v24, v100, v22
	v_addc_co_u32_e32 v27, vcc, 0, v21, vcc
	v_add_co_u32_e32 v38, vcc, s13, v20
	s_waitcnt lgkmcnt(0)
	v_pk_add_f32 v[22:23], v[22:23], v[24:25]
	ds_bpermute_b32 v37, v101, v23
	ds_bpermute_b32 v36, v101, v22
	v_addc_co_u32_e32 v39, vcc, 0, v21, vcc
	s_mov_b32 s13, 0x23000
	v_add_co_u32_e32 v20, vcc, s13, v20
	s_waitcnt lgkmcnt(0)
	v_pk_add_f32 v[22:23], v[22:23], v[36:37]
	ds_bpermute_b32 v37, v102, v23
	ds_bpermute_b32 v36, v102, v22
	v_addc_co_u32_e32 v21, vcc, 0, v21, vcc
	global_load_dwordx4 v[60:63], v[28:29], off offset:3072
	s_nop 0
	global_load_dwordx4 v[28:31], v[28:29], off offset:1024
	s_nop 0
	global_load_dwordx4 v[48:51], v[26:27], off offset:3328
	s_nop 0
	global_load_dwordx4 v[24:27], v[26:27], off offset:1280
	s_waitcnt lgkmcnt(0)
	v_pk_add_f32 v[22:23], v[22:23], v[36:37]
	ds_bpermute_b32 v41, v103, v23
	ds_bpermute_b32 v40, v103, v22
	global_load_dwordx4 v[64:67], v[38:39], off offset:3584
	s_nop 0
	global_load_dwordx4 v[36:39], v[38:39], off offset:1536
	s_waitcnt vmcnt(11)
	v_lshlrev_b32_e32 v120, 16, v16
	v_lshlrev_b32_e32 v112, 16, v19
	v_and_b32_e32 v113, 0xffff0000, v19
	s_waitcnt lgkmcnt(0)
	v_pk_add_f32 v[22:23], v[22:23], v[40:41]
	ds_bpermute_b32 v109, v104, v23
	ds_bpermute_b32 v108, v104, v22
	global_load_dwordx4 v[52:55], v[20:21], off offset:3840
	global_load_dwordx4 v[40:43], v[20:21], off offset:1792
	v_and_b32_e32 v121, 0xffff0000, v16
	v_add_f32_e32 v16, 0, v120
	v_lshlrev_b32_e32 v118, 16, v17
	s_waitcnt lgkmcnt(0)
	v_pk_add_f32 v[20:21], v[22:23], v[108:109]
	v_add_f32_e32 v107, v16, v121
	v_pk_mul_f32 v[116:117], v[20:21], s[40:41] op_sel_hi:[1,0]
	v_mul_f32_e32 v22, v121, v121
	v_fma_f32 v19, -v117, v117, v116
	v_max_f32_e32 v19, 0, v19
	v_add_f32_e32 v19, 0x358637bd, v19
	v_and_b32_e32 v119, 0xffff0000, v17
	v_mov_b32_e32 v16, v118
	v_mov_b32_e32 v17, v121
	v_pk_fma_f32 v[22:23], v[120:121], v[120:121], v[22:23] op_sel_hi:[1,1,0]
	v_add_f32_e32 v107, v107, v118
	v_lshlrev_b32_e32 v114, 16, v18
	v_mul_f32_e32 v20, 0x4b800000, v19
	v_cmp_gt_f32_e32 vcc, s19, v19
	v_pk_fma_f32 v[16:17], v[16:17], v[16:17], v[22:23]
	v_add_f32_e32 v23, v107, v119
	v_mul_f32_e32 v22, v119, v119
	v_cndmask_b32_e32 v19, v19, v20, vcc
	v_and_b32_e32 v115, 0xffff0000, v18
	v_mov_b32_e32 v20, v114
	v_mov_b32_e32 v21, v119
	v_pk_add_f32 v[16:17], v[22:23], v[16:17] op_sel_hi:[0,1]
	v_add_f32_e32 v22, v23, v114
	v_pk_fma_f32 v[16:17], v[20:21], v[20:21], v[16:17]
	v_add_f32_e32 v21, v22, v115
	v_mul_f32_e32 v20, v115, v115
	v_rsq_f32_e32 v87, v19
	v_mov_b32_e32 v18, v112
	v_mov_b32_e32 v19, v115
	v_pk_add_f32 v[16:17], v[20:21], v[16:17] op_sel_hi:[0,1]
	v_pk_fma_f32 v[16:17], v[18:19], v[18:19], v[16:17]
	v_add_f32_e32 v21, v21, v112
	v_mul_f32_e32 v20, v113, v113
	v_mov_b32_e32 v17, v113
	v_pk_add_f32 v[108:109], v[20:21], v[16:17]
	ds_bpermute_b32 v111, v100, v109
	ds_bpermute_b32 v110, v100, v108
	global_load_dwordx2 v[20:21], v[88:89], off offset:128
	global_load_dwordx2 v[22:23], v[88:89], off offset:160
	global_load_dwordx2 v[16:17], v[88:89], off offset:192
	global_load_dwordx2 v[18:19], v[88:89], off offset:224
	v_mul_f32_e32 v107, 0x45800000, v87
	v_cndmask_b32_e32 v122, v87, v107, vcc
	v_pk_add_f32 v[96:97], v[96:97], v[116:117] op_sel:[0,1] neg_lo:[0,1] neg_hi:[0,1]
	s_waitcnt lgkmcnt(0)
	v_pk_add_f32 v[88:89], v[108:109], v[110:111]
	ds_bpermute_b32 v109, v101, v89
	ds_bpermute_b32 v108, v101, v88
	v_pk_mul_f32 v[96:97], v[96:97], v[122:123] op_sel_hi:[1,0]
	v_pk_add_f32 v[94:95], v[94:95], v[116:117] op_sel:[0,1] neg_lo:[0,1] neg_hi:[0,1]
	v_pk_mul_f32 v[96:97], v[12:13], v[96:97]
	v_pk_mul_f32 v[94:95], v[94:95], v[122:123] op_sel_hi:[1,0]
	s_waitcnt lgkmcnt(0)
	v_pk_add_f32 v[88:89], v[88:89], v[108:109]
	ds_bpermute_b32 v111, v102, v89
	ds_bpermute_b32 v110, v102, v88
	v_cvt_pk_bf16_f32 v108, v96, v97
	v_pk_mul_f32 v[94:95], v[14:15], v[94:95]
	v_pk_add_f32 v[92:93], v[92:93], v[116:117] op_sel:[0,1] neg_lo:[0,1] neg_hi:[0,1]
	v_cvt_pk_bf16_f32 v109, v94, v95
	s_waitcnt lgkmcnt(0)
	v_pk_add_f32 v[88:89], v[88:89], v[110:111]
	ds_bpermute_b32 v97, v103, v89
	ds_bpermute_b32 v96, v103, v88
	v_pk_add_f32 v[90:91], v[90:91], v[116:117] op_sel:[0,1] neg_lo:[0,1] neg_hi:[0,1]
	v_pk_mul_f32 v[92:93], v[92:93], v[122:123] op_sel_hi:[1,0]
	v_pk_mul_f32 v[90:91], v[90:91], v[122:123] op_sel_hi:[1,0]
	s_waitcnt vmcnt(15)
	v_lshlrev_b32_e32 v122, 16, v76
	s_waitcnt lgkmcnt(0)
	v_pk_add_f32 v[88:89], v[88:89], v[96:97]
	ds_bpermute_b32 v95, v104, v89
	ds_bpermute_b32 v94, v104, v88
	v_and_b32_e32 v123, 0xffff0000, v76
	v_lshlrev_b32_e32 v96, 16, v77
	v_add_f32_e32 v76, 0, v122
	v_mul_f32_e32 v124, v123, v123
	s_waitcnt lgkmcnt(0)
	v_pk_add_f32 v[88:89], v[88:89], v[94:95]
	v_and_b32_e32 v97, 0xffff0000, v77
	v_pk_mul_f32 v[88:89], v[88:89], s[40:41] op_sel_hi:[1,0]
	v_add_f32_e32 v107, v76, v123
	v_fma_f32 v87, -v89, v89, v88
	v_max_f32_e32 v87, 0, v87
	v_mov_b32_e32 v76, v96
	v_mov_b32_e32 v77, v123
	v_pk_fma_f32 v[124:125], v[122:123], v[122:123], v[124:125] op_sel_hi:[1,1,0]
	v_pk_mul_f32 v[92:93], v[8:9], v[92:93]
	v_add_f32_e32 v87, 0x358637bd, v87
	v_lshlrev_b32_e32 v94, 16, v78
	v_pk_fma_f32 v[76:77], v[76:77], v[76:77], v[124:125]
	v_mul_f32_e32 v124, v97, v97
	v_cvt_pk_bf16_f32 v110, v92, v93
	v_mul_f32_e32 v92, 0x4b800000, v87
	v_cmp_gt_f32_e32 vcc, s19, v87
	v_and_b32_e32 v95, 0xffff0000, v78
	v_mov_b32_e32 v116, v94
	v_mov_b32_e32 v117, v97
	v_add_f32_e32 v107, v107, v96
	v_pk_add_f32 v[76:77], v[124:125], v[76:77] op_sel_hi:[0,1]
	v_cndmask_b32_e32 v87, v87, v92, vcc
	v_lshlrev_b32_e32 v92, 16, v79
	v_add_f32_e32 v107, v107, v97
	v_pk_fma_f32 v[76:77], v[116:117], v[116:117], v[76:77]
	v_mul_f32_e32 v116, v95, v95
	v_and_b32_e32 v93, 0xffff0000, v79
	v_mov_b32_e32 v78, v92
	v_mov_b32_e32 v79, v95
	v_add_f32_e32 v107, v107, v94
	v_pk_add_f32 v[76:77], v[116:117], v[76:77] op_sel_hi:[0,1]
	v_add_f32_e32 v107, v107, v95
	v_pk_fma_f32 v[76:77], v[78:79], v[78:79], v[76:77]
	v_add_f32_e32 v117, v107, v92
	v_mul_f32_e32 v116, v93, v93
	v_mov_b32_e32 v77, v93
	v_pk_add_f32 v[76:77], v[116:117], v[76:77]
	ds_bpermute_b32 v79, v100, v77
	ds_bpermute_b32 v78, v100, v76
	v_pk_mul_f32 v[90:91], v[10:11], v[90:91]
	v_rsq_f32_e32 v87, v87
	v_cvt_pk_bf16_f32 v111, v90, v91
	ds_write_b128 v105, v[108:111]
	ds_write_b128 v106, v[72:75]
	s_waitcnt lgkmcnt(2)
	v_pk_add_f32 v[72:73], v[76:77], v[78:79]
	ds_bpermute_b32 v75, v101, v73
	ds_bpermute_b32 v74, v101, v72
	v_mul_f32_e32 v90, 0x45800000, v87
	v_cndmask_b32_e32 v76, v87, v90, vcc
	v_pk_add_f32 v[78:79], v[120:121], v[88:89] op_sel:[0,1] neg_lo:[0,1] neg_hi:[0,1]
	s_waitcnt lgkmcnt(0)
	v_pk_add_f32 v[74:75], v[72:73], v[74:75]
	ds_bpermute_b32 v91, v102, v75
	ds_bpermute_b32 v90, v102, v74
	v_pk_mul_f32 v[78:79], v[78:79], v[76:77] op_sel_hi:[1,0]
	s_waitcnt lgkmcnt(0)
	v_pk_add_f32 v[74:75], v[74:75], v[90:91]
	ds_bpermute_b32 v91, v103, v75
	ds_bpermute_b32 v90, v103, v74
	v_pk_mul_f32 v[78:79], v[12:13], v[78:79]
	s_waitcnt lgkmcnt(0)
	v_pk_add_f32 v[90:91], v[74:75], v[90:91]
	v_cvt_pk_bf16_f32 v72, v78, v79
	v_pk_add_f32 v[78:79], v[118:119], v[88:89] op_sel:[0,1] neg_lo:[0,1] neg_hi:[0,1]
	ds_bpermute_b32 v109, v104, v91
	v_pk_mul_f32 v[78:79], v[78:79], v[76:77] op_sel_hi:[1,0]
	ds_bpermute_b32 v108, v104, v90
	v_pk_mul_f32 v[78:79], v[14:15], v[78:79]
	s_nop 0
	v_cvt_pk_bf16_f32 v73, v78, v79
	v_pk_add_f32 v[78:79], v[114:115], v[88:89] op_sel:[0,1] neg_lo:[0,1] neg_hi:[0,1]
	s_nop 0
	v_pk_mul_f32 v[78:79], v[78:79], v[76:77] op_sel_hi:[1,0]
	s_nop 0
	v_pk_mul_f32 v[78:79], v[8:9], v[78:79]
	s_nop 0
	v_cvt_pk_bf16_f32 v74, v78, v79
	v_pk_add_f32 v[78:79], v[112:113], v[88:89] op_sel:[0,1] neg_lo:[0,1] neg_hi:[0,1]
	s_waitcnt vmcnt(13)
	v_lshlrev_b32_e32 v112, 16, v68
	v_pk_mul_f32 v[76:77], v[78:79], v[76:77] op_sel_hi:[1,0]
	s_waitcnt lgkmcnt(0)
	v_pk_add_f32 v[78:79], v[90:91], v[108:109]
	v_and_b32_e32 v113, 0xffff0000, v68
	v_pk_mul_f32 v[78:79], v[78:79], s[40:41] op_sel_hi:[1,0]
	v_lshlrev_b32_e32 v108, 16, v69
	v_fma_f32 v75, -v79, v79, v78
	v_max_f32_e32 v75, 0, v75
	v_add_f32_e32 v75, 0x358637bd, v75
	v_mul_f32_e32 v87, 0x4b800000, v75
	v_cmp_gt_f32_e32 vcc, s19, v75
	v_add_f32_e32 v68, 0, v112
	v_mul_f32_e32 v114, v113, v113
	v_cndmask_b32_e32 v75, v75, v87, vcc
	v_rsq_f32_e32 v87, v75
	v_and_b32_e32 v109, 0xffff0000, v69
	v_add_f32_e32 v75, v68, v113
	v_mov_b32_e32 v68, v108
	v_mov_b32_e32 v69, v113
	v_pk_fma_f32 v[114:115], v[112:113], v[112:113], v[114:115] op_sel_hi:[1,1,0]
	v_lshlrev_b32_e32 v90, 16, v70
	v_pk_fma_f32 v[68:69], v[68:69], v[68:69], v[114:115]
	v_mul_f32_e32 v114, v109, v109
	v_and_b32_e32 v91, 0xffff0000, v70
	v_mov_b32_e32 v110, v90
	v_mov_b32_e32 v111, v109
	v_add_f32_e32 v75, v75, v108
	v_pk_add_f32 v[68:69], v[114:115], v[68:69] op_sel_hi:[0,1]
	v_lshlrev_b32_e32 v88, 16, v71
	v_add_f32_e32 v75, v75, v109
	v_pk_fma_f32 v[68:69], v[110:111], v[110:111], v[68:69]
	v_mul_f32_e32 v110, v91, v91
	v_and_b32_e32 v89, 0xffff0000, v71
	v_mov_b32_e32 v70, v88
	v_mov_b32_e32 v71, v91
	v_add_f32_e32 v75, v75, v90
	v_pk_add_f32 v[68:69], v[110:111], v[68:69] op_sel_hi:[0,1]
	v_add_f32_e32 v75, v75, v91
	v_pk_fma_f32 v[68:69], v[70:71], v[70:71], v[68:69]
	v_add_f32_e32 v111, v75, v88
	v_mul_f32_e32 v110, v89, v89
	v_mov_b32_e32 v69, v89
	v_pk_add_f32 v[68:69], v[110:111], v[68:69]
	ds_bpermute_b32 v71, v100, v69
	ds_bpermute_b32 v70, v100, v68
	v_pk_mul_f32 v[76:77], v[10:11], v[76:77]
	s_nop 0
	v_cvt_pk_bf16_f32 v75, v76, v77
	ds_write_b128 v105, v[72:75] offset:1088
	ds_write_b128 v106, v[56:59] offset:1088
	s_waitcnt lgkmcnt(2)
	v_pk_add_f32 v[56:57], v[68:69], v[70:71]
	ds_bpermute_b32 v59, v101, v57
	ds_bpermute_b32 v58, v101, v56
	v_mul_f32_e32 v72, 0x45800000, v87
	v_cndmask_b32_e32 v68, v87, v72, vcc
	v_pk_add_f32 v[70:71], v[122:123], v[78:79] op_sel:[0,1] neg_lo:[0,1] neg_hi:[0,1]
	s_waitcnt vmcnt(11)
	v_lshlrev_b32_e32 v76, 16, v61
	s_waitcnt lgkmcnt(0)
	v_pk_add_f32 v[58:59], v[56:57], v[58:59]
	ds_bpermute_b32 v73, v102, v59
	ds_bpermute_b32 v72, v102, v58
	v_pk_mul_f32 v[70:71], v[70:71], v[68:69] op_sel_hi:[1,0]
	v_and_b32_e32 v77, 0xffff0000, v61
	v_pk_mul_f32 v[70:71], v[12:13], v[70:71]
	s_waitcnt lgkmcnt(0)
	v_pk_add_f32 v[58:59], v[58:59], v[72:73]
	ds_bpermute_b32 v73, v103, v59
	ds_bpermute_b32 v72, v103, v58
	v_cvt_pk_bf16_f32 v56, v70, v71
	v_pk_add_f32 v[70:71], v[96:97], v[78:79] op_sel:[0,1] neg_lo:[0,1] neg_hi:[0,1]
	s_waitcnt lgkmcnt(0)
	v_pk_add_f32 v[72:73], v[58:59], v[72:73]
	v_pk_mul_f32 v[70:71], v[70:71], v[68:69] op_sel_hi:[1,0]
	ds_bpermute_b32 v75, v104, v73
	v_pk_mul_f32 v[70:71], v[14:15], v[70:71]
	ds_bpermute_b32 v74, v104, v72
	v_cvt_pk_bf16_f32 v57, v70, v71
	v_pk_add_f32 v[70:71], v[94:95], v[78:79] op_sel:[0,1] neg_lo:[0,1] neg_hi:[0,1]
	s_nop 0
	v_pk_mul_f32 v[70:71], v[70:71], v[68:69] op_sel_hi:[1,0]
	s_nop 0
	v_pk_mul_f32 v[70:71], v[8:9], v[70:71]
	s_nop 0
	v_cvt_pk_bf16_f32 v58, v70, v71
	v_pk_add_f32 v[70:71], v[92:93], v[78:79] op_sel:[0,1] neg_lo:[0,1] neg_hi:[0,1]
	v_and_b32_e32 v93, 0xffff0000, v60
	v_pk_mul_f32 v[68:69], v[70:71], v[68:69] op_sel_hi:[1,0]
	s_waitcnt lgkmcnt(0)
	v_pk_add_f32 v[70:71], v[72:73], v[74:75]
	v_lshlrev_b32_e32 v92, 16, v60
	v_pk_mul_f32 v[70:71], v[70:71], s[40:41] op_sel_hi:[1,0]
	v_mul_f32_e32 v94, v93, v93
	v_fma_f32 v59, -v71, v71, v70
	v_max_f32_e32 v59, 0, v59
	v_add_f32_e32 v59, 0x358637bd, v59
	v_mul_f32_e32 v72, 0x4b800000, v59
	v_cmp_gt_f32_e32 vcc, s19, v59
	v_mov_b32_e32 v60, v76
	v_mov_b32_e32 v61, v93
	v_cndmask_b32_e32 v59, v59, v72, vcc
	v_rsq_f32_e32 v87, v59
	v_add_f32_e32 v59, 0, v92
	v_pk_fma_f32 v[94:95], v[92:93], v[92:93], v[94:95] op_sel_hi:[1,1,0]
	v_lshlrev_b32_e32 v74, 16, v62
	v_add_f32_e32 v59, v59, v93
	v_pk_fma_f32 v[60:61], v[60:61], v[60:61], v[94:95]
	v_mul_f32_e32 v94, v77, v77
	v_and_b32_e32 v75, 0xffff0000, v62
	v_mov_b32_e32 v78, v74
	v_mov_b32_e32 v79, v77
	v_add_f32_e32 v59, v59, v76
	v_pk_add_f32 v[60:61], v[94:95], v[60:61] op_sel_hi:[0,1]
	v_lshlrev_b32_e32 v72, 16, v63
	v_add_f32_e32 v59, v59, v77
	v_pk_fma_f32 v[60:61], v[78:79], v[78:79], v[60:61]
	v_mul_f32_e32 v78, v75, v75
	v_and_b32_e32 v73, 0xffff0000, v63
	v_mov_b32_e32 v62, v72
	v_mov_b32_e32 v63, v75
	v_add_f32_e32 v59, v59, v74
	v_pk_add_f32 v[60:61], v[78:79], v[60:61] op_sel_hi:[0,1]
	v_add_f32_e32 v59, v59, v75
	v_pk_fma_f32 v[60:61], v[62:63], v[62:63], v[60:61]
	v_add_f32_e32 v79, v59, v72
	v_mul_f32_e32 v78, v73, v73
	v_mov_b32_e32 v61, v73
	v_pk_add_f32 v[60:61], v[78:79], v[60:61]
	ds_bpermute_b32 v63, v100, v61
	ds_bpermute_b32 v62, v100, v60
	v_pk_mul_f32 v[68:69], v[10:11], v[68:69]
	s_waitcnt vmcnt(9)
	v_and_b32_e32 v79, 0xffff0000, v48
	v_cvt_pk_bf16_f32 v59, v68, v69
	ds_write_b128 v105, v[56:59] offset:2176
	ds_write_b128 v106, v[44:47] offset:2176
	s_waitcnt lgkmcnt(2)
	v_pk_add_f32 v[44:45], v[60:61], v[62:63]
	ds_bpermute_b32 v47, v101, v45
	ds_bpermute_b32 v46, v101, v44
	v_mul_f32_e32 v56, 0x45800000, v87
	v_cndmask_b32_e32 v56, v87, v56, vcc
	v_pk_add_f32 v[58:59], v[112:113], v[70:71] op_sel:[0,1] neg_lo:[0,1] neg_hi:[0,1]
	v_lshlrev_b32_e32 v68, 16, v49
	s_waitcnt lgkmcnt(0)
	v_pk_add_f32 v[46:47], v[44:45], v[46:47]
	ds_bpermute_b32 v61, v102, v47
	ds_bpermute_b32 v60, v102, v46
	v_pk_mul_f32 v[58:59], v[58:59], v[56:57] op_sel_hi:[1,0]
	v_lshlrev_b32_e32 v78, 16, v48
	v_pk_mul_f32 v[58:59], v[12:13], v[58:59]
	v_and_b32_e32 v69, 0xffff0000, v49
	s_waitcnt lgkmcnt(0)
	v_pk_add_f32 v[46:47], v[46:47], v[60:61]
	ds_bpermute_b32 v61, v103, v47
	ds_bpermute_b32 v60, v103, v46
	v_cvt_pk_bf16_f32 v44, v58, v59
	v_pk_add_f32 v[58:59], v[108:109], v[70:71] op_sel:[0,1] neg_lo:[0,1] neg_hi:[0,1]
	v_mov_b32_e32 v48, v68
	v_pk_mul_f32 v[58:59], v[58:59], v[56:57] op_sel_hi:[1,0]
	s_waitcnt lgkmcnt(0)
	v_pk_add_f32 v[60:61], v[46:47], v[60:61]
	v_pk_mul_f32 v[58:59], v[14:15], v[58:59]
	ds_bpermute_b32 v63, v104, v61
	ds_bpermute_b32 v62, v104, v60
	v_cvt_pk_bf16_f32 v45, v58, v59
	v_pk_add_f32 v[58:59], v[90:91], v[70:71] op_sel:[0,1] neg_lo:[0,1] neg_hi:[0,1]
	v_mov_b32_e32 v49, v79
	v_pk_mul_f32 v[58:59], v[58:59], v[56:57] op_sel_hi:[1,0]
	s_nop 0
	v_pk_mul_f32 v[58:59], v[8:9], v[58:59]
	s_nop 0
	v_cvt_pk_bf16_f32 v46, v58, v59
	v_pk_add_f32 v[58:59], v[88:89], v[70:71] op_sel:[0,1] neg_lo:[0,1] neg_hi:[0,1]
	v_mul_f32_e32 v88, v79, v79
	v_pk_mul_f32 v[56:57], v[58:59], v[56:57] op_sel_hi:[1,0]
	s_waitcnt lgkmcnt(0)
	v_pk_add_f32 v[58:59], v[60:61], v[62:63]
	v_pk_fma_f32 v[88:89], v[78:79], v[78:79], v[88:89] op_sel_hi:[1,1,0]
	v_pk_mul_f32 v[58:59], v[58:59], s[40:41] op_sel_hi:[1,0]
	v_lshlrev_b32_e32 v62, 16, v50
	v_fma_f32 v47, -v59, v59, v58
	v_max_f32_e32 v47, 0, v47
	v_add_f32_e32 v47, 0x358637bd, v47
	v_mul_f32_e32 v60, 0x4b800000, v47
	v_cmp_gt_f32_e32 vcc, s19, v47
	v_pk_fma_f32 v[48:49], v[48:49], v[48:49], v[88:89]
	v_mul_f32_e32 v88, v69, v69
	v_cndmask_b32_e32 v47, v47, v60, vcc
	v_rsq_f32_e32 v87, v47
	v_add_f32_e32 v47, 0, v78
	v_add_f32_e32 v47, v47, v79
	v_and_b32_e32 v63, 0xffff0000, v50
	v_mov_b32_e32 v70, v62
	v_mov_b32_e32 v71, v69
	v_add_f32_e32 v47, v47, v68
	v_pk_add_f32 v[48:49], v[88:89], v[48:49] op_sel_hi:[0,1]
	v_lshlrev_b32_e32 v60, 16, v51
	v_add_f32_e32 v47, v47, v69
	v_pk_fma_f32 v[48:49], v[70:71], v[70:71], v[48:49]
	v_mul_f32_e32 v70, v63, v63
	v_and_b32_e32 v61, 0xffff0000, v51
	v_mov_b32_e32 v50, v60
	v_mov_b32_e32 v51, v63
	v_add_f32_e32 v47, v47, v62
	v_pk_add_f32 v[48:49], v[70:71], v[48:49] op_sel_hi:[0,1]
	v_add_f32_e32 v47, v47, v63
	v_pk_fma_f32 v[48:49], v[50:51], v[50:51], v[48:49]
	v_add_f32_e32 v71, v47, v60
	v_mul_f32_e32 v70, v61, v61
	v_mov_b32_e32 v49, v61
	v_pk_add_f32 v[48:49], v[70:71], v[48:49]
	ds_bpermute_b32 v51, v100, v49
	ds_bpermute_b32 v50, v100, v48
	v_pk_mul_f32 v[56:57], v[10:11], v[56:57]
	s_waitcnt vmcnt(7)
	v_and_b32_e32 v71, 0xffff0000, v64
	v_cvt_pk_bf16_f32 v47, v56, v57
	ds_write_b128 v105, v[44:47] offset:3264
	ds_write_b128 v106, v[32:35] offset:3264
	s_waitcnt lgkmcnt(2)
	v_pk_add_f32 v[32:33], v[48:49], v[50:51]
	ds_bpermute_b32 v35, v101, v33
	ds_bpermute_b32 v34, v101, v32
	v_mul_f32_e32 v44, 0x45800000, v87
	v_cndmask_b32_e32 v44, v87, v44, vcc
	v_pk_add_f32 v[46:47], v[92:93], v[58:59] op_sel:[0,1] neg_lo:[0,1] neg_hi:[0,1]
	v_lshlrev_b32_e32 v70, 16, v64
	s_waitcnt lgkmcnt(0)
	v_pk_add_f32 v[34:35], v[32:33], v[34:35]
	ds_bpermute_b32 v49, v102, v35
	ds_bpermute_b32 v48, v102, v34
	v_pk_mul_f32 v[46:47], v[46:47], v[44:45] op_sel_hi:[1,0]
	s_waitcnt lgkmcnt(0)
	v_pk_add_f32 v[34:35], v[34:35], v[48:49]
	ds_bpermute_b32 v49, v103, v35
	ds_bpermute_b32 v48, v103, v34
	v_pk_mul_f32 v[46:47], v[12:13], v[46:47]
	s_waitcnt lgkmcnt(0)
	v_pk_add_f32 v[48:49], v[34:35], v[48:49]
	v_cvt_pk_bf16_f32 v32, v46, v47
	v_pk_add_f32 v[46:47], v[76:77], v[58:59] op_sel:[0,1] neg_lo:[0,1] neg_hi:[0,1]
	ds_bpermute_b32 v51, v104, v49
	v_pk_mul_f32 v[46:47], v[46:47], v[44:45] op_sel_hi:[1,0]
	ds_bpermute_b32 v50, v104, v48
	v_pk_mul_f32 v[46:47], v[14:15], v[46:47]
	s_nop 0
	v_cvt_pk_bf16_f32 v33, v46, v47
	v_pk_add_f32 v[46:47], v[74:75], v[58:59] op_sel:[0,1] neg_lo:[0,1] neg_hi:[0,1]
	s_nop 0
	v_pk_mul_f32 v[46:47], v[46:47], v[44:45] op_sel_hi:[1,0]
	s_nop 0
	v_pk_mul_f32 v[46:47], v[8:9], v[46:47]
	s_nop 0
	v_cvt_pk_bf16_f32 v34, v46, v47
	v_pk_add_f32 v[46:47], v[72:73], v[58:59] op_sel:[0,1] neg_lo:[0,1] neg_hi:[0,1]
	v_lshlrev_b32_e32 v58, 16, v65
	v_pk_mul_f32 v[44:45], v[46:47], v[44:45] op_sel_hi:[1,0]
	s_waitcnt lgkmcnt(0)
	v_pk_add_f32 v[46:47], v[48:49], v[50:51]
	v_mul_f32_e32 v72, v71, v71
	v_pk_mul_f32 v[46:47], v[46:47], s[40:41] op_sel_hi:[1,0]
	v_and_b32_e32 v59, 0xffff0000, v65
	v_fma_f32 v35, -v47, v47, v46
	v_max_f32_e32 v35, 0, v35
	v_add_f32_e32 v35, 0x358637bd, v35
	v_mul_f32_e32 v48, 0x4b800000, v35
	v_cmp_gt_f32_e32 vcc, s19, v35
	v_mov_b32_e32 v64, v58
	v_mov_b32_e32 v65, v71
	v_cndmask_b32_e32 v35, v35, v48, vcc
	v_rsq_f32_e32 v74, v35
	v_add_f32_e32 v35, 0, v70
	v_pk_fma_f32 v[72:73], v[70:71], v[70:71], v[72:73] op_sel_hi:[1,1,0]
	v_lshlrev_b32_e32 v50, 16, v66
	v_add_f32_e32 v35, v35, v71
	v_pk_fma_f32 v[64:65], v[64:65], v[64:65], v[72:73]
	v_mul_f32_e32 v72, v59, v59
	v_lshlrev_b32_e32 v48, 16, v67
	v_and_b32_e32 v49, 0xffff0000, v67
	v_and_b32_e32 v51, 0xffff0000, v66
	v_mov_b32_e32 v66, v50
	v_mov_b32_e32 v67, v59
	v_add_f32_e32 v35, v35, v58
	v_pk_add_f32 v[64:65], v[72:73], v[64:65] op_sel_hi:[0,1]
	v_add_f32_e32 v35, v35, v59
	v_pk_fma_f32 v[64:65], v[66:67], v[66:67], v[64:65]
	v_mul_f32_e32 v66, v51, v51
	v_mov_b32_e32 v56, v48
	v_mov_b32_e32 v57, v51
	v_add_f32_e32 v35, v35, v50
	v_pk_add_f32 v[64:65], v[66:67], v[64:65] op_sel_hi:[0,1]
	v_add_f32_e32 v35, v35, v51
	v_pk_fma_f32 v[56:57], v[56:57], v[56:57], v[64:65]
	v_add_f32_e32 v67, v35, v48
	v_mul_f32_e32 v66, v49, v49
	v_mov_b32_e32 v57, v49
	v_pk_add_f32 v[56:57], v[66:67], v[56:57]
	ds_bpermute_b32 v65, v100, v57
	ds_bpermute_b32 v64, v100, v56
	v_pk_mul_f32 v[44:45], v[10:11], v[44:45]
	s_nop 0
	v_cvt_pk_bf16_f32 v35, v44, v45
	ds_write_b128 v105, v[32:35] offset:4352
	ds_write_b128 v106, v[28:31] offset:4352
	s_waitcnt lgkmcnt(2)
	v_pk_add_f32 v[28:29], v[56:57], v[64:65]
	ds_bpermute_b32 v31, v101, v29
	ds_bpermute_b32 v30, v101, v28
	v_mul_f32_e32 v32, 0x45800000, v74
	v_cndmask_b32_e32 v32, v74, v32, vcc
	v_pk_add_f32 v[34:35], v[78:79], v[46:47] op_sel:[0,1] neg_lo:[0,1] neg_hi:[0,1]
	s_waitcnt lgkmcnt(0)
	v_pk_add_f32 v[30:31], v[28:29], v[30:31]
	ds_bpermute_b32 v45, v102, v31
	ds_bpermute_b32 v44, v102, v30
	v_pk_mul_f32 v[34:35], v[34:35], v[32:33] op_sel_hi:[1,0]
	s_waitcnt lgkmcnt(0)
	v_pk_add_f32 v[30:31], v[30:31], v[44:45]
	ds_bpermute_b32 v45, v103, v31
	ds_bpermute_b32 v44, v103, v30
	v_pk_mul_f32 v[34:35], v[12:13], v[34:35]
	s_waitcnt lgkmcnt(0)
	v_pk_add_f32 v[44:45], v[30:31], v[44:45]
	v_cvt_pk_bf16_f32 v28, v34, v35
	v_pk_add_f32 v[34:35], v[68:69], v[46:47] op_sel:[0,1] neg_lo:[0,1] neg_hi:[0,1]
	ds_bpermute_b32 v57, v104, v45
	v_pk_mul_f32 v[34:35], v[34:35], v[32:33] op_sel_hi:[1,0]
	ds_bpermute_b32 v56, v104, v44
	v_pk_mul_f32 v[34:35], v[14:15], v[34:35]
	s_nop 0
	v_cvt_pk_bf16_f32 v29, v34, v35
	v_pk_add_f32 v[34:35], v[62:63], v[46:47] op_sel:[0,1] neg_lo:[0,1] neg_hi:[0,1]
	s_waitcnt vmcnt(5)
	v_and_b32_e32 v63, 0xffff0000, v52
	v_pk_mul_f32 v[34:35], v[34:35], v[32:33] op_sel_hi:[1,0]
	v_lshlrev_b32_e32 v62, 16, v52
	v_pk_mul_f32 v[34:35], v[8:9], v[34:35]
	v_mul_f32_e32 v64, v63, v63
	v_cvt_pk_bf16_f32 v30, v34, v35
	v_pk_add_f32 v[34:35], v[60:61], v[46:47] op_sel:[0,1] neg_lo:[0,1] neg_hi:[0,1]
	v_pk_fma_f32 v[64:65], v[62:63], v[62:63], v[64:65] op_sel_hi:[1,1,0]
	v_pk_mul_f32 v[32:33], v[34:35], v[32:33] op_sel_hi:[1,0]
	s_waitcnt lgkmcnt(0)
	v_pk_add_f32 v[34:35], v[44:45], v[56:57]
	v_lshlrev_b32_e32 v56, 16, v53
	v_pk_mul_f32 v[34:35], v[34:35], s[40:41] op_sel_hi:[1,0]
	v_and_b32_e32 v57, 0xffff0000, v53
	v_fma_f32 v31, -v35, v35, v34
	v_max_f32_e32 v31, 0, v31
	v_add_f32_e32 v31, 0x358637bd, v31
	v_mul_f32_e32 v44, 0x4b800000, v31
	v_cmp_gt_f32_e32 vcc, s19, v31
	v_mov_b32_e32 v52, v56
	v_mov_b32_e32 v53, v63
	v_cndmask_b32_e32 v31, v31, v44, vcc
	v_rsq_f32_e32 v66, v31
	v_add_f32_e32 v31, 0, v62
	v_lshlrev_b32_e32 v46, 16, v54
	v_add_f32_e32 v31, v31, v63
	v_pk_fma_f32 v[52:53], v[52:53], v[52:53], v[64:65]
	v_mul_f32_e32 v64, v57, v57
	v_and_b32_e32 v47, 0xffff0000, v54
	v_mov_b32_e32 v60, v46
	v_mov_b32_e32 v61, v57
	v_add_f32_e32 v31, v31, v56
	v_pk_add_f32 v[52:53], v[64:65], v[52:53] op_sel_hi:[0,1]
	v_lshlrev_b32_e32 v44, 16, v55
	v_add_f32_e32 v31, v31, v57
	v_pk_fma_f32 v[52:53], v[60:61], v[60:61], v[52:53]
	v_mul_f32_e32 v60, v47, v47
	v_and_b32_e32 v45, 0xffff0000, v55
	v_mov_b32_e32 v54, v44
	v_mov_b32_e32 v55, v47
	v_add_f32_e32 v31, v31, v46
	v_pk_add_f32 v[52:53], v[60:61], v[52:53] op_sel_hi:[0,1]
	v_add_f32_e32 v31, v31, v47
	v_pk_fma_f32 v[52:53], v[54:55], v[54:55], v[52:53]
	v_add_f32_e32 v61, v31, v44
	v_mul_f32_e32 v60, v45, v45
	v_mov_b32_e32 v53, v45
	v_pk_add_f32 v[52:53], v[60:61], v[52:53]
	ds_bpermute_b32 v55, v100, v53
	ds_bpermute_b32 v54, v100, v52
	v_pk_mul_f32 v[32:33], v[10:11], v[32:33]
	s_nop 0
	v_cvt_pk_bf16_f32 v31, v32, v33
	ds_write_b128 v105, v[28:31] offset:5440
	ds_write_b128 v106, v[24:27] offset:5440
	s_waitcnt lgkmcnt(2)
	v_pk_add_f32 v[24:25], v[52:53], v[54:55]
	ds_bpermute_b32 v27, v101, v25
	ds_bpermute_b32 v26, v101, v24
	v_mul_f32_e32 v28, 0x45800000, v66
	v_cndmask_b32_e32 v28, v66, v28, vcc
	v_pk_add_f32 v[30:31], v[70:71], v[34:35] op_sel:[0,1] neg_lo:[0,1] neg_hi:[0,1]
	s_waitcnt lgkmcnt(0)
	v_pk_add_f32 v[26:27], v[24:25], v[26:27]
	ds_bpermute_b32 v33, v102, v27
	ds_bpermute_b32 v32, v102, v26
	v_pk_mul_f32 v[30:31], v[30:31], v[28:29] op_sel_hi:[1,0]
	s_waitcnt lgkmcnt(0)
	v_pk_add_f32 v[26:27], v[26:27], v[32:33]
	ds_bpermute_b32 v33, v103, v27
	ds_bpermute_b32 v32, v103, v26
	v_pk_mul_f32 v[30:31], v[12:13], v[30:31]
	s_waitcnt lgkmcnt(0)
	v_pk_add_f32 v[32:33], v[26:27], v[32:33]
	v_cvt_pk_bf16_f32 v24, v30, v31
	v_pk_add_f32 v[30:31], v[58:59], v[34:35] op_sel:[0,1] neg_lo:[0,1] neg_hi:[0,1]
	s_nop 0
	v_pk_mul_f32 v[30:31], v[30:31], v[28:29] op_sel_hi:[1,0]
	s_nop 0
	v_pk_mul_f32 v[30:31], v[14:15], v[30:31]
	s_nop 0
	v_cvt_pk_bf16_f32 v25, v30, v31
	v_pk_add_f32 v[30:31], v[50:51], v[34:35] op_sel:[0,1] neg_lo:[0,1] neg_hi:[0,1]
	ds_bpermute_b32 v51, v104, v33
	ds_bpermute_b32 v50, v104, v32
	v_pk_mul_f32 v[30:31], v[30:31], v[28:29] op_sel_hi:[1,0]
	s_nop 0
	v_pk_mul_f32 v[30:31], v[8:9], v[30:31]
	s_nop 0
	v_cvt_pk_bf16_f32 v26, v30, v31
	v_pk_add_f32 v[30:31], v[48:49], v[34:35] op_sel:[0,1] neg_lo:[0,1] neg_hi:[0,1]
	s_nop 0
	v_pk_mul_f32 v[28:29], v[30:31], v[28:29] op_sel_hi:[1,0]
	s_waitcnt lgkmcnt(0)
	v_pk_add_f32 v[30:31], v[32:33], v[50:51]
	v_pk_mul_f32 v[28:29], v[10:11], v[28:29]
	v_pk_mul_f32 v[30:31], v[30:31], s[40:41] op_sel_hi:[1,0]
	s_nop 0
	v_fma_f32 v27, -v31, v31, v30
	v_max_f32_e32 v27, 0, v27
	v_add_f32_e32 v27, 0x358637bd, v27
	v_mul_f32_e32 v32, 0x4b800000, v27
	v_cmp_gt_f32_e32 vcc, s19, v27
	s_nop 1
	v_cndmask_b32_e32 v27, v27, v32, vcc
	v_rsq_f32_e32 v32, v27
	v_cvt_pk_bf16_f32 v27, v28, v29
	ds_write_b128 v105, v[24:27] offset:6528
	ds_write_b128 v106, v[36:39] offset:6528
	v_pk_add_f32 v[26:27], v[62:63], v[30:31] op_sel:[0,1] neg_lo:[0,1] neg_hi:[0,1]
	v_mul_f32_e32 v24, 0x45800000, v32
	v_cndmask_b32_e32 v24, v32, v24, vcc
	v_pk_mul_f32 v[26:27], v[26:27], v[24:25] op_sel_hi:[1,0]
	s_nop 0
	v_pk_mul_f32 v[12:13], v[12:13], v[26:27]
	v_pk_add_f32 v[26:27], v[56:57], v[30:31] op_sel:[0,1] neg_lo:[0,1] neg_hi:[0,1]
	v_cvt_pk_bf16_f32 v12, v12, v13
	v_pk_mul_f32 v[26:27], v[26:27], v[24:25] op_sel_hi:[1,0]
	s_nop 0
	v_pk_mul_f32 v[14:15], v[14:15], v[26:27]
	s_nop 0
	v_cvt_pk_bf16_f32 v13, v14, v15
	v_pk_add_f32 v[14:15], v[46:47], v[30:31] op_sel:[0,1] neg_lo:[0,1] neg_hi:[0,1]
	s_nop 0
	v_pk_mul_f32 v[14:15], v[14:15], v[24:25] op_sel_hi:[1,0]
	s_nop 0
	v_pk_mul_f32 v[8:9], v[8:9], v[14:15]
	s_nop 0
	v_cvt_pk_bf16_f32 v14, v8, v9
	v_pk_add_f32 v[8:9], v[44:45], v[30:31] op_sel:[0,1] neg_lo:[0,1] neg_hi:[0,1]
	s_nop 0
	v_pk_mul_f32 v[8:9], v[8:9], v[24:25] op_sel_hi:[1,0]
	s_nop 0
	v_pk_mul_f32 v[8:9], v[10:11], v[8:9]
	s_nop 0
	v_cvt_pk_bf16_f32 v15, v8, v9
	v_lshl_add_u32 v8, s11, 7, v80
	v_ashrrev_i32_e32 v9, 31, v8
	v_lshl_add_u64 v[8:9], v[8:9], 2, s[54:55]
	ds_write_b128 v105, v[12:15] offset:7616
	s_waitcnt vmcnt(4)
	ds_write_b128 v106, v[40:43] offset:7616
	s_waitcnt lgkmcnt(0)
	s_barrier
	global_load_dword v28, v[8:9], off
	ds_read_b64_tr_b16 v[8:9], v99
	ds_read_b64_tr_b16 v[12:13], v99 offset:32
	ds_read_b64_tr_b16 v[24:25], v99 offset:64
	ds_read_b64_tr_b16 v[30:31], v99 offset:96
	ds_read_b64_tr_b16 v[10:11], v99 offset:8704
	ds_read_b64_tr_b16 v[14:15], v99 offset:8736
	ds_read_b64_tr_b16 v[26:27], v99 offset:8768
	ds_read_b64_tr_b16 v[32:33], v99 offset:8800
	ds_read_b64_tr_b16 v[34:35], v99 offset:128
	ds_read_b64_tr_b16 v[38:39], v99 offset:160
	ds_read_b64_tr_b16 v[42:43], v99 offset:192
	ds_read_b64_tr_b16 v[46:47], v99 offset:224
	ds_read_b64_tr_b16 v[36:37], v99 offset:8832
	ds_read_b64_tr_b16 v[40:41], v99 offset:8864
	ds_read_b64_tr_b16 v[44:45], v99 offset:8896
	ds_read_b64_tr_b16 v[48:49], v99 offset:8928
	ds_read_b64_tr_b16 v[50:51], v99 offset:256
	ds_read_b64_tr_b16 v[54:55], v99 offset:288
	ds_read_b64_tr_b16 v[58:59], v99 offset:320
	ds_read_b64_tr_b16 v[62:63], v99 offset:352
	ds_read_b64_tr_b16 v[52:53], v99 offset:8960
	ds_read_b64_tr_b16 v[56:57], v99 offset:8992
	ds_read_b64_tr_b16 v[60:61], v99 offset:9024
	ds_read_b64_tr_b16 v[64:65], v99 offset:9056
	ds_read_b64_tr_b16 v[66:67], v99 offset:384
	ds_read_b64_tr_b16 v[70:71], v99 offset:416
	ds_read_b64_tr_b16 v[74:75], v99 offset:448
	ds_read_b64_tr_b16 v[88:89], v99 offset:480
	ds_read_b64_tr_b16 v[68:69], v99 offset:9088
	ds_read_b64_tr_b16 v[72:73], v99 offset:9120
	ds_read_b64_tr_b16 v[76:77], v99 offset:9152
	ds_read_b64_tr_b16 v[90:91], v99 offset:9184
	ds_read_b64_tr_b16 v[92:93], v99 offset:17408
	ds_read_b64_tr_b16 v[108:109], v99 offset:17440
	ds_read_b64_tr_b16 v[112:113], v99 offset:17472
	ds_read_b64_tr_b16 v[116:117], v99 offset:17504
	ds_read_b64_tr_b16 v[94:95], v99 offset:26112
	ds_read_b64_tr_b16 v[110:111], v99 offset:26144
	ds_read_b64_tr_b16 v[114:115], v99 offset:26176
	ds_read_b64_tr_b16 v[118:119], v99 offset:26208
	ds_read_b64_tr_b16 v[120:121], v99 offset:17536
	ds_read_b64_tr_b16 v[124:125], v99 offset:17568
	ds_read_b64_tr_b16 v[128:129], v99 offset:17600
	ds_read_b64_tr_b16 v[132:133], v99 offset:17632
	ds_read_b64_tr_b16 v[122:123], v99 offset:26240
	ds_read_b64_tr_b16 v[126:127], v99 offset:26272
	ds_read_b64_tr_b16 v[130:131], v99 offset:26304
	ds_read_b64_tr_b16 v[134:135], v99 offset:26336
	ds_read_b64_tr_b16 v[136:137], v99 offset:17664
	ds_read_b64_tr_b16 v[140:141], v99 offset:17696
	ds_read_b64_tr_b16 v[144:145], v99 offset:17728
	ds_read_b64_tr_b16 v[148:149], v99 offset:17760
	ds_read_b64_tr_b16 v[138:139], v99 offset:26368
	ds_read_b64_tr_b16 v[142:143], v99 offset:26400
	ds_read_b64_tr_b16 v[146:147], v99 offset:26432
	ds_read_b64_tr_b16 v[150:151], v99 offset:26464
	ds_read_b64_tr_b16 v[156:157], v99 offset:17792
	ds_read_b64_tr_b16 v[160:161], v99 offset:17824
	ds_read_b64_tr_b16 v[164:165], v99 offset:17856
	ds_read_b64_tr_b16 v[168:169], v99 offset:17888
	ds_read_b64_tr_b16 v[158:159], v99 offset:26496
	ds_read_b64_tr_b16 v[162:163], v99 offset:26528
	ds_read_b64_tr_b16 v[166:167], v99 offset:26560
	ds_read_b64_tr_b16 v[170:171], v99 offset:26592
	s_waitcnt lgkmcnt(14)
	v_mfma_f32_16x16x32_bf16 v[8:11], v[8:11], v[4:7], 0
	v_mfma_f32_16x16x32_bf16 v[12:15], v[12:15], v[4:7], 0
	v_mfma_f32_16x16x32_bf16 v[24:27], v[24:27], v[4:7], 0
	v_mfma_f32_16x16x32_bf16 v[30:33], v[30:33], v[4:7], 0
	v_mfma_f32_16x16x32_bf16 v[34:37], v[34:37], v[4:7], 0
	v_mfma_f32_16x16x32_bf16 v[38:41], v[38:41], v[4:7], 0
	v_mfma_f32_16x16x32_bf16 v[42:45], v[42:45], v[4:7], 0
	v_mfma_f32_16x16x32_bf16 v[46:49], v[46:49], v[4:7], 0
	v_mfma_f32_16x16x32_bf16 v[50:53], v[50:53], v[4:7], 0
	v_mfma_f32_16x16x32_bf16 v[54:57], v[54:57], v[4:7], 0
	v_mfma_f32_16x16x32_bf16 v[58:61], v[58:61], v[4:7], 0
	v_mfma_f32_16x16x32_bf16 v[62:65], v[62:65], v[4:7], 0
	v_mfma_f32_16x16x32_bf16 v[66:69], v[66:69], v[4:7], 0
	v_mfma_f32_16x16x32_bf16 v[70:73], v[70:73], v[4:7], 0
	v_mfma_f32_16x16x32_bf16 v[74:77], v[74:77], v[4:7], 0
	v_mfma_f32_16x16x32_bf16 v[4:7], v[88:91], v[4:7], 0
	ds_read_b64_tr_b16 v[88:89], v99 offset:34816
	ds_read_b64_tr_b16 v[172:173], v99 offset:34848
	ds_read_b64_tr_b16 v[178:179], v99 offset:34880
	ds_read_b64_tr_b16 v[182:183], v99 offset:34912
	ds_read_b64_tr_b16 v[90:91], v99 offset:43520
	ds_read_b64_tr_b16 v[174:175], v99 offset:43552
	ds_read_b64_tr_b16 v[180:181], v99 offset:43584
	ds_read_b64_tr_b16 v[184:185], v99 offset:43616
	ds_read_b64_tr_b16 v[188:189], v99 offset:34944
	ds_read_b64_tr_b16 v[192:193], v99 offset:34976
	ds_read_b64_tr_b16 v[202:203], v99 offset:35008
	ds_read_b64_tr_b16 v[206:207], v99 offset:35040
	ds_read_b64_tr_b16 v[190:191], v99 offset:43648
	ds_read_b64_tr_b16 v[194:195], v99 offset:43680
	ds_read_b64_tr_b16 v[204:205], v99 offset:43712
	ds_read_b64_tr_b16 v[208:209], v99 offset:43744
	ds_read_b64_tr_b16 v[210:211], v99 offset:35072
	ds_read_b64_tr_b16 v[214:215], v99 offset:35104
	ds_read_b64_tr_b16 v[218:219], v99 offset:35136
	ds_read_b64_tr_b16 v[222:223], v99 offset:35168
	ds_read_b64_tr_b16 v[212:213], v99 offset:43776
	ds_read_b64_tr_b16 v[216:217], v99 offset:43808
	ds_read_b64_tr_b16 v[220:221], v99 offset:43840
	ds_read_b64_tr_b16 v[224:225], v99 offset:43872
	ds_read_b64_tr_b16 v[226:227], v99 offset:35200
	ds_read_b64_tr_b16 v[230:231], v99 offset:35232
	ds_read_b64_tr_b16 v[234:235], v99 offset:35264
	ds_read_b64_tr_b16 v[238:239], v99 offset:35296
	ds_read_b64_tr_b16 v[228:229], v99 offset:43904
	ds_read_b64_tr_b16 v[232:233], v99 offset:43936
	ds_read_b64_tr_b16 v[236:237], v99 offset:43968
	ds_read_b64_tr_b16 v[240:241], v99 offset:44000
	v_mfma_f32_16x16x32_bf16 v[8:11], v[92:95], v[0:3], v[8:11]
	v_mfma_f32_16x16x32_bf16 v[12:15], v[108:111], v[0:3], v[12:15]
	v_mfma_f32_16x16x32_bf16 v[24:27], v[112:115], v[0:3], v[24:27]
	v_mfma_f32_16x16x32_bf16 v[30:33], v[116:119], v[0:3], v[30:33]
	v_mfma_f32_16x16x32_bf16 v[34:37], v[120:123], v[0:3], v[34:37]
	v_mfma_f32_16x16x32_bf16 v[38:41], v[124:127], v[0:3], v[38:41]
	v_mfma_f32_16x16x32_bf16 v[42:45], v[128:131], v[0:3], v[42:45]
	v_mfma_f32_16x16x32_bf16 v[46:49], v[132:135], v[0:3], v[46:49]
	s_waitcnt lgkmcnt(14)
	v_mfma_f32_16x16x32_bf16 v[50:53], v[136:139], v[0:3], v[50:53]
	v_mfma_f32_16x16x32_bf16 v[54:57], v[140:143], v[0:3], v[54:57]
	v_mfma_f32_16x16x32_bf16 v[58:61], v[144:147], v[0:3], v[58:61]
	v_mfma_f32_16x16x32_bf16 v[62:65], v[148:151], v[0:3], v[62:65]
	v_mfma_f32_16x16x32_bf16 v[66:69], v[156:159], v[0:3], v[66:69]
	v_mfma_f32_16x16x32_bf16 v[70:73], v[160:163], v[0:3], v[70:73]
	v_mfma_f32_16x16x32_bf16 v[74:77], v[164:167], v[0:3], v[74:77]
	v_mfma_f32_16x16x32_bf16 v[0:3], v[168:171], v[0:3], v[4:7]
	s_nop 2
	ds_read_b64_tr_b16 v[4:5], v99 offset:52224
	ds_read_b64_tr_b16 v[92:93], v99 offset:52256
	ds_read_b64_tr_b16 v[108:109], v99 offset:52288
	ds_read_b64_tr_b16 v[112:113], v99 offset:52320
	ds_read_b64_tr_b16 v[6:7], v99 offset:60928
	ds_read_b64_tr_b16 v[94:95], v99 offset:60960
	ds_read_b64_tr_b16 v[110:111], v99 offset:60992
	ds_read_b64_tr_b16 v[114:115], v99 offset:61024
	ds_read_b64_tr_b16 v[116:117], v99 offset:52352
	ds_read_b64_tr_b16 v[120:121], v99 offset:52384
	ds_read_b64_tr_b16 v[124:125], v99 offset:52416
	ds_read_b64_tr_b16 v[128:129], v99 offset:52448
	ds_read_b64_tr_b16 v[118:119], v99 offset:61056
	ds_read_b64_tr_b16 v[122:123], v99 offset:61088
	ds_read_b64_tr_b16 v[126:127], v99 offset:61120
	ds_read_b64_tr_b16 v[130:131], v99 offset:61152
	ds_read_b64_tr_b16 v[132:133], v99 offset:52480
	ds_read_b64_tr_b16 v[136:137], v99 offset:52512
	ds_read_b64_tr_b16 v[140:141], v99 offset:52544
	ds_read_b64_tr_b16 v[144:145], v99 offset:52576
	ds_read_b64_tr_b16 v[134:135], v99 offset:61184
	ds_read_b64_tr_b16 v[138:139], v99 offset:61216
	ds_read_b64_tr_b16 v[142:143], v99 offset:61248
	ds_read_b64_tr_b16 v[146:147], v99 offset:61280
	ds_read_b64_tr_b16 v[148:149], v99 offset:52608
	ds_read_b64_tr_b16 v[156:157], v99 offset:52640
	ds_read_b64_tr_b16 v[160:161], v99 offset:52672
	ds_read_b64_tr_b16 v[164:165], v99 offset:52704
	ds_read_b64_tr_b16 v[150:151], v99 offset:61312
	ds_read_b64_tr_b16 v[158:159], v99 offset:61344
	ds_read_b64_tr_b16 v[162:163], v99 offset:61376
	ds_read_b64_tr_b16 v[166:167], v99 offset:61408
	s_waitcnt vmcnt(3)
	v_mfma_f32_16x16x32_bf16 v[8:11], v[88:91], v[20:23], v[8:11]
	v_mfma_f32_16x16x32_bf16 v[12:15], v[172:175], v[20:23], v[12:15]
	v_mfma_f32_16x16x32_bf16 v[24:27], v[178:181], v[20:23], v[24:27]
	v_mfma_f32_16x16x32_bf16 v[30:33], v[182:185], v[20:23], v[30:33]
	v_mfma_f32_16x16x32_bf16 v[34:37], v[188:191], v[20:23], v[34:37]
	v_mfma_f32_16x16x32_bf16 v[38:41], v[192:195], v[20:23], v[38:41]
	v_mfma_f32_16x16x32_bf16 v[42:45], v[202:205], v[20:23], v[42:45]
	v_mfma_f32_16x16x32_bf16 v[46:49], v[206:209], v[20:23], v[46:49]
	s_waitcnt lgkmcnt(14)
	v_mfma_f32_16x16x32_bf16 v[50:53], v[210:213], v[20:23], v[50:53]
	v_mfma_f32_16x16x32_bf16 v[54:57], v[214:217], v[20:23], v[54:57]
	v_mfma_f32_16x16x32_bf16 v[58:61], v[218:221], v[20:23], v[58:61]
	v_mfma_f32_16x16x32_bf16 v[62:65], v[222:225], v[20:23], v[62:65]
	v_mfma_f32_16x16x32_bf16 v[66:69], v[226:229], v[20:23], v[66:69]
	v_mfma_f32_16x16x32_bf16 v[70:73], v[230:233], v[20:23], v[70:73]
	v_mfma_f32_16x16x32_bf16 v[74:77], v[234:237], v[20:23], v[74:77]
	v_mfma_f32_16x16x32_bf16 v[0:3], v[238:241], v[20:23], v[0:3]
	s_waitcnt vmcnt(1)
	v_mfma_f32_16x16x32_bf16 v[88:91], v[4:7], v[16:19], v[8:11]
	v_mfma_f32_16x16x32_bf16 v[92:95], v[92:95], v[16:19], v[12:15]
	v_mfma_f32_16x16x32_bf16 v[108:111], v[108:111], v[16:19], v[24:27]
	v_mfma_f32_16x16x32_bf16 v[30:33], v[112:115], v[16:19], v[30:33]
	v_mfma_f32_16x16x32_bf16 v[34:37], v[116:119], v[16:19], v[34:37]
	v_mfma_f32_16x16x32_bf16 v[38:41], v[120:123], v[16:19], v[38:41]
	v_mfma_f32_16x16x32_bf16 v[42:45], v[124:127], v[16:19], v[42:45]
	v_mfma_f32_16x16x32_bf16 v[46:49], v[128:131], v[16:19], v[46:49]
	s_waitcnt lgkmcnt(11)
	v_mfma_f32_16x16x32_bf16 v[50:53], v[132:135], v[16:19], v[50:53]
	s_waitcnt lgkmcnt(10)
	v_mfma_f32_16x16x32_bf16 v[54:57], v[136:139], v[16:19], v[54:57]
	s_waitcnt lgkmcnt(9)
	v_mfma_f32_16x16x32_bf16 v[24:27], v[140:143], v[16:19], v[58:61]
	s_waitcnt lgkmcnt(8)
	v_mfma_f32_16x16x32_bf16 v[20:23], v[144:147], v[16:19], v[62:65]
	s_waitcnt lgkmcnt(3)
	v_mfma_f32_16x16x32_bf16 v[12:15], v[148:151], v[16:19], v[66:69]
	s_waitcnt lgkmcnt(2)
	v_mfma_f32_16x16x32_bf16 v[8:11], v[156:159], v[16:19], v[70:73]
	s_waitcnt lgkmcnt(1)
	v_mfma_f32_16x16x32_bf16 v[4:7], v[160:163], v[16:19], v[74:77]
	s_waitcnt lgkmcnt(0)
	v_mfma_f32_16x16x32_bf16 v[0:3], v[164:167], v[16:19], v[0:3]
	ds_read2_b64 v[58:61], v81 offset1:4
	v_add_u32_e32 v18, s10, v80
	v_mov_b64_e32 v[16:17], s[38:39]
	v_mad_i64_i32 v[16:17], s[10:11], v18, s34, v[16:17]
	s_waitcnt lgkmcnt(0)
	v_lshlrev_b32_e32 v18, 16, v58
	v_and_b32_e32 v19, 0xffff0000, v58
	s_waitcnt vmcnt(0)
	v_pk_add_f32 v[62:63], v[28:29], v[88:89] op_sel_hi:[0,1]
	v_pk_mul_f32 v[18:19], v[62:63], v[18:19]
	v_lshlrev_b32_e32 v58, 16, v59
	v_and_b32_e32 v59, 0xffff0000, v59
	v_pk_add_f32 v[62:63], v[28:29], v[90:91] op_sel_hi:[0,1]
	v_lshl_add_u64 v[16:17], v[16:17], 0, s[8:9]
	v_mov_b32_e32 v87, v155
	v_pk_mul_f32 v[58:59], v[62:63], v[58:59]
	v_lshl_add_u64 v[16:17], v[16:17], 0, v[86:87]
	v_cvt_pk_bf16_f32 v18, v18, v19
	v_cvt_pk_bf16_f32 v19, v58, v59
	ds_write_b64 v81, v[18:19]
	v_lshlrev_b32_e32 v18, 16, v60
	v_and_b32_e32 v19, 0xffff0000, v60
	v_pk_add_f32 v[58:59], v[28:29], v[92:93] op_sel_hi:[0,1]
	v_pk_mul_f32 v[18:19], v[58:59], v[18:19]
	v_lshlrev_b32_e32 v62, 16, v61
	v_and_b32_e32 v63, 0xffff0000, v61
	ds_read2_b64 v[58:61], v81 offset0:8 offset1:12
	v_pk_add_f32 v[64:65], v[28:29], v[94:95] op_sel_hi:[0,1]
	v_pk_mul_f32 v[62:63], v[64:65], v[62:63]
	v_cvt_pk_bf16_f32 v18, v18, v19
	v_cvt_pk_bf16_f32 v19, v62, v63
	ds_write_b64 v81, v[18:19] offset:32
	s_waitcnt lgkmcnt(0)
	v_lshlrev_b32_e32 v18, 16, v58
	v_and_b32_e32 v19, 0xffff0000, v58
	v_pk_add_f32 v[62:63], v[28:29], v[108:109] op_sel_hi:[0,1]
	v_pk_mul_f32 v[18:19], v[62:63], v[18:19]
	v_lshlrev_b32_e32 v58, 16, v59
	v_and_b32_e32 v59, 0xffff0000, v59
	v_pk_add_f32 v[62:63], v[28:29], v[110:111] op_sel_hi:[0,1]
	v_pk_mul_f32 v[58:59], v[62:63], v[58:59]
	v_cvt_pk_bf16_f32 v18, v18, v19
	v_cvt_pk_bf16_f32 v19, v58, v59
	ds_write_b64 v81, v[18:19] offset:64
	v_lshlrev_b32_e32 v18, 16, v60
	v_and_b32_e32 v19, 0xffff0000, v60
	v_pk_add_f32 v[30:31], v[28:29], v[30:31] op_sel_hi:[0,1]
	v_pk_mul_f32 v[18:19], v[30:31], v[18:19]
	v_lshlrev_b32_e32 v30, 16, v61
	v_and_b32_e32 v31, 0xffff0000, v61
	ds_read2_b64 v[58:61], v81 offset0:16 offset1:20
	v_pk_add_f32 v[32:33], v[28:29], v[32:33] op_sel_hi:[0,1]
	v_pk_mul_f32 v[30:31], v[32:33], v[30:31]
	v_cvt_pk_bf16_f32 v18, v18, v19
	v_cvt_pk_bf16_f32 v19, v30, v31
	ds_write_b64 v81, v[18:19] offset:96
	s_waitcnt lgkmcnt(0)
	v_lshlrev_b32_e32 v18, 16, v58
	v_and_b32_e32 v19, 0xffff0000, v58
	v_pk_add_f32 v[30:31], v[28:29], v[34:35] op_sel_hi:[0,1]
	v_pk_mul_f32 v[18:19], v[30:31], v[18:19]
	v_lshlrev_b32_e32 v30, 16, v59
	v_and_b32_e32 v31, 0xffff0000, v59
	v_pk_add_f32 v[32:33], v[28:29], v[36:37] op_sel_hi:[0,1]
	v_pk_mul_f32 v[30:31], v[32:33], v[30:31]
	v_cvt_pk_bf16_f32 v18, v18, v19
	v_cvt_pk_bf16_f32 v19, v30, v31
	ds_write_b64 v81, v[18:19] offset:128
	v_lshlrev_b32_e32 v18, 16, v60
	v_and_b32_e32 v19, 0xffff0000, v60
	v_pk_add_f32 v[30:31], v[28:29], v[38:39] op_sel_hi:[0,1]
	v_pk_mul_f32 v[18:19], v[30:31], v[18:19]
	ds_read2_b64 v[30:33], v81 offset0:24 offset1:28
	v_lshlrev_b32_e32 v34, 16, v61
	v_and_b32_e32 v35, 0xffff0000, v61
	v_pk_add_f32 v[36:37], v[28:29], v[40:41] op_sel_hi:[0,1]
	v_pk_mul_f32 v[34:35], v[36:37], v[34:35]
	v_cvt_pk_bf16_f32 v18, v18, v19
	v_cvt_pk_bf16_f32 v19, v34, v35
	ds_write_b64 v81, v[18:19] offset:160
	s_waitcnt lgkmcnt(0)
	v_lshlrev_b32_e32 v18, 16, v30
	v_and_b32_e32 v19, 0xffff0000, v30
	v_pk_add_f32 v[34:35], v[28:29], v[42:43] op_sel_hi:[0,1]
	v_pk_mul_f32 v[18:19], v[34:35], v[18:19]
	v_lshlrev_b32_e32 v30, 16, v31
	v_and_b32_e32 v31, 0xffff0000, v31
	v_pk_add_f32 v[34:35], v[28:29], v[44:45] op_sel_hi:[0,1]
	v_pk_mul_f32 v[30:31], v[34:35], v[30:31]
	v_cvt_pk_bf16_f32 v18, v18, v19
	v_cvt_pk_bf16_f32 v19, v30, v31
	ds_write_b64 v81, v[18:19] offset:192
	v_lshlrev_b32_e32 v18, 16, v32
	v_and_b32_e32 v19, 0xffff0000, v32
	v_pk_add_f32 v[30:31], v[28:29], v[46:47] op_sel_hi:[0,1]
	v_pk_mul_f32 v[18:19], v[30:31], v[18:19]
	v_lshlrev_b32_e32 v34, 16, v33
	v_and_b32_e32 v35, 0xffff0000, v33
	ds_read2_b64 v[30:33], v81 offset0:32 offset1:36
	v_pk_add_f32 v[36:37], v[28:29], v[48:49] op_sel_hi:[0,1]
	v_pk_mul_f32 v[34:35], v[36:37], v[34:35]
	v_cvt_pk_bf16_f32 v18, v18, v19
	v_cvt_pk_bf16_f32 v19, v34, v35
	ds_write_b64 v81, v[18:19] offset:224
	s_waitcnt lgkmcnt(0)
	v_lshlrev_b32_e32 v18, 16, v30
	v_and_b32_e32 v19, 0xffff0000, v30
	v_pk_add_f32 v[34:35], v[28:29], v[50:51] op_sel_hi:[0,1]
	v_pk_mul_f32 v[18:19], v[34:35], v[18:19]
	v_lshlrev_b32_e32 v30, 16, v31
	v_and_b32_e32 v31, 0xffff0000, v31
	v_pk_add_f32 v[34:35], v[28:29], v[52:53] op_sel_hi:[0,1]
	v_pk_mul_f32 v[30:31], v[34:35], v[30:31]
	v_cvt_pk_bf16_f32 v18, v18, v19
	v_cvt_pk_bf16_f32 v19, v30, v31
	ds_read2_b64 v[34:37], v81 offset0:40 offset1:44
	ds_write_b64 v81, v[18:19] offset:256
	v_lshlrev_b32_e32 v18, 16, v32
	v_and_b32_e32 v19, 0xffff0000, v32
	v_pk_add_f32 v[30:31], v[28:29], v[54:55] op_sel_hi:[0,1]
	v_pk_mul_f32 v[18:19], v[30:31], v[18:19]
	v_lshlrev_b32_e32 v30, 16, v33
	v_and_b32_e32 v31, 0xffff0000, v33
	v_pk_add_f32 v[32:33], v[28:29], v[56:57] op_sel_hi:[0,1]
	v_pk_mul_f32 v[30:31], v[32:33], v[30:31]
	v_cvt_pk_bf16_f32 v18, v18, v19
	v_cvt_pk_bf16_f32 v19, v30, v31
	ds_write_b64 v81, v[18:19] offset:288
	s_waitcnt lgkmcnt(0)
	v_lshlrev_b32_e32 v18, 16, v34
	v_and_b32_e32 v19, 0xffff0000, v34
	v_pk_add_f32 v[24:25], v[28:29], v[24:25] op_sel_hi:[0,1]
	v_pk_mul_f32 v[18:19], v[24:25], v[18:19]
	v_lshlrev_b32_e32 v24, 16, v35
	v_and_b32_e32 v25, 0xffff0000, v35
	v_pk_add_f32 v[26:27], v[28:29], v[26:27] op_sel_hi:[0,1]
	v_pk_mul_f32 v[24:25], v[26:27], v[24:25]
	v_cvt_pk_bf16_f32 v18, v18, v19
	v_cvt_pk_bf16_f32 v19, v24, v25
	ds_write_b64 v81, v[18:19] offset:320
	v_lshlrev_b32_e32 v18, 16, v36
	v_and_b32_e32 v19, 0xffff0000, v36
	v_pk_add_f32 v[20:21], v[28:29], v[20:21] op_sel_hi:[0,1]
	v_pk_mul_f32 v[18:19], v[20:21], v[18:19]
	v_lshlrev_b32_e32 v26, 16, v37
	v_cvt_pk_bf16_f32 v24, v18, v19
	ds_read2_b64 v[18:21], v81 offset0:48 offset1:52
	v_and_b32_e32 v27, 0xffff0000, v37
	v_pk_add_f32 v[22:23], v[28:29], v[22:23] op_sel_hi:[0,1]
	v_pk_mul_f32 v[22:23], v[22:23], v[26:27]
	v_pk_add_f32 v[12:13], v[28:29], v[12:13] op_sel_hi:[0,1]
	v_cvt_pk_bf16_f32 v25, v22, v23
	s_waitcnt lgkmcnt(0)
	v_lshlrev_b32_e32 v22, 16, v18
	v_and_b32_e32 v23, 0xffff0000, v18
	v_lshlrev_b32_e32 v18, 16, v19
	v_and_b32_e32 v19, 0xffff0000, v19
	v_pk_add_f32 v[14:15], v[28:29], v[14:15] op_sel_hi:[0,1]
	v_pk_mul_f32 v[12:13], v[12:13], v[22:23]
	v_pk_mul_f32 v[14:15], v[14:15], v[18:19]
	v_cvt_pk_bf16_f32 v12, v12, v13
	v_cvt_pk_bf16_f32 v13, v14, v15
	ds_write_b64 v81, v[12:13] offset:384
	v_lshlrev_b32_e32 v12, 16, v20
	v_and_b32_e32 v13, 0xffff0000, v20
	v_pk_add_f32 v[8:9], v[28:29], v[8:9] op_sel_hi:[0,1]
	v_pk_mul_f32 v[8:9], v[8:9], v[12:13]
	ds_read2_b64 v[12:15], v81 offset0:56 offset1:60
	v_lshlrev_b32_e32 v18, 16, v21
	v_and_b32_e32 v19, 0xffff0000, v21
	v_pk_add_f32 v[10:11], v[28:29], v[10:11] op_sel_hi:[0,1]
	v_pk_mul_f32 v[10:11], v[10:11], v[18:19]
	v_cvt_pk_bf16_f32 v8, v8, v9
	v_cvt_pk_bf16_f32 v9, v10, v11
	ds_write_b64 v81, v[8:9] offset:416
	s_waitcnt lgkmcnt(0)
	v_lshlrev_b32_e32 v8, 16, v12
	v_and_b32_e32 v9, 0xffff0000, v12
	v_pk_add_f32 v[4:5], v[28:29], v[4:5] op_sel_hi:[0,1]
	v_pk_mul_f32 v[4:5], v[4:5], v[8:9]
	v_lshlrev_b32_e32 v8, 16, v13
	v_and_b32_e32 v9, 0xffff0000, v13
	v_pk_add_f32 v[6:7], v[28:29], v[6:7] op_sel_hi:[0,1]
	v_pk_mul_f32 v[6:7], v[6:7], v[8:9]
	v_cvt_pk_bf16_f32 v4, v4, v5
	v_cvt_pk_bf16_f32 v5, v6, v7
	ds_write_b64 v81, v[4:5] offset:448
	v_lshlrev_b32_e32 v4, 16, v14
	v_and_b32_e32 v5, 0xffff0000, v14
	v_pk_add_f32 v[0:1], v[28:29], v[0:1] op_sel_hi:[0,1]
	v_pk_mul_f32 v[0:1], v[0:1], v[4:5]
	v_lshlrev_b32_e32 v4, 16, v15
	v_and_b32_e32 v5, 0xffff0000, v15
	v_pk_add_f32 v[2:3], v[28:29], v[2:3] op_sel_hi:[0,1]
	v_pk_mul_f32 v[2:3], v[2:3], v[4:5]
	s_add_i32 s3, s3, s94
	s_add_i32 s2, s2, s30
	v_cvt_pk_bf16_f32 v0, v0, v1
	v_cvt_pk_bf16_f32 v1, v2, v3
	s_cmpk_gt_i32 s3, 0x1ff
	ds_write_b64 v81, v[24:25] offset:352
	ds_write_b64 v81, v[0:1] offset:480
	v_readfirstlane_b32 s98, v16
	v_readfirstlane_b32 s99, v17
	v_readfirstlane_b32 s100, v81
	s_nop 0
	v_add_u32_e32 v250, s100, v249
	s_waitcnt lgkmcnt(0)
	ds_read_b128 v[0:3], v250
	ds_read_b128 v[4:7], v250 offset:1088
	ds_read_b128 v[8:11], v250 offset:2176
	ds_read_b128 v[12:15], v250 offset:3264
	ds_read_b128 v[16:19], v250 offset:4352
	ds_read_b128 v[20:23], v250 offset:5440
	ds_read_b128 v[24:27], v250 offset:6528
	ds_read_b128 v[28:31], v250 offset:7616
	s_waitcnt lgkmcnt(7)
	global_store_dwordx4 v248, v[0:3], s[98:99] sc1
	s_waitcnt lgkmcnt(6)
	s_add_u32 s98, s98, 0x2100
	s_addc_u32 s99, s99, 0
	global_store_dwordx4 v248, v[4:7], s[98:99] sc1
	s_waitcnt lgkmcnt(5)
	s_add_u32 s98, s98, 0x2100
	s_addc_u32 s99, s99, 0
	global_store_dwordx4 v248, v[8:11], s[98:99] sc1
	s_waitcnt lgkmcnt(4)
	s_add_u32 s98, s98, 0x2100
	s_addc_u32 s99, s99, 0
	global_store_dwordx4 v248, v[12:15], s[98:99] sc1
	s_waitcnt lgkmcnt(3)
	s_add_u32 s98, s98, 0x2100
	s_addc_u32 s99, s99, 0
	global_store_dwordx4 v248, v[16:19], s[98:99] sc1
	s_waitcnt lgkmcnt(2)
	s_add_u32 s98, s98, 0x2100
	s_addc_u32 s99, s99, 0
	global_store_dwordx4 v248, v[20:23], s[98:99] sc1
	s_waitcnt lgkmcnt(1)
	s_add_u32 s98, s98, 0x2100
	s_addc_u32 s99, s99, 0
	global_store_dwordx4 v248, v[24:27], s[98:99] sc1
	s_waitcnt lgkmcnt(0)
	s_add_u32 s98, s98, 0x2100
	s_addc_u32 s99, s99, 0
	global_store_dwordx4 v248, v[28:31], s[98:99] sc1
	s_cmpk_gt_i32 s3, 0x1ff
	s_barrier
	s_cbranch_scc0 .LBB0_125
